# plus: removed redundant canonicalising v_max x,x,x before relu in the indexer passes (bit-identical for non-sNaN), re-padded MFMA distances
# speedup vs baseline: 1.0716x; 1.0175x over previous
; DI void phase_ffnup(const Params& p, int layer, unsigned char* smem) {
;     ...
;   for (int it = vblock(); it < NTILES; it += gridDim.x) {
;     const int g = it / (4 * NT), rem = it - g * (4 * NT), nt = rem >> 2, mt = g * 4 + (rem & 3);
;     const int b = mt / 17, ti = mt - b * 17, tbase = 254 * ti - 2;
;     f32x4 acc[8][4];
;     zero_acc<4, 8>(acc);
;     gemm_kloop<4, 8>(p.hb + ((ptrdiff_t)(b * TP + tbase)) * DM, DM, W + (size_t)(nt * 256) * DM, DM, DM, acc, smem);
.LBB0_23:
	s_mul_hi_i32 s2, s28, 0x2e8ba2e9
	s_lshr_b32 s3, s2, 31
	s_ashr_i32 s2, s2, 4
	s_add_i32 s53, s2, s3
	s_mul_i32 s2, s53, 0xffffffa8
	s_add_i32 s2, s2, s28
	s_ashr_i32 s34, s2, 2
	s_lshl_b32 s2, s53, 2
	s_and_b32 s3, s28, 3
	s_or_b32 s2, s2, s3
	s_mul_hi_i32 s3, s2, 0x78787879
	s_lshr_b32 s4, s3, 31
	s_ashr_i32 s3, s3, 3
	s_add_i32 s54, s3, s4
	s_mul_i32 s3, s54, 0xffffffef
	s_add_i32 s3, s3, s2
	s_mulk_i32 s3, 0xfe
	s_load_dwordx16 s[56:71], s[0:1], 0xc8
	s_add_i32 s35, s3, -2
	s_mul_i32 s2, s54, 0x1080
	v_mov_b32_e32 v52, v166
	s_add_i32 s4, s35, s2
	s_ashr_i32 s5, s4, 31
	v_lshlrev_b32_e32 v2, 3, v52
	v_ashrrev_i32_e32 v53, 3, v52
	v_and_b32_e32 v2, 56, v2
	s_and_b32 s52, s31, 3
	s_lshl_b64 s[4:5], s[4:5], 11
	v_lshl_or_b32 v2, v53, 10, v2
	s_waitcnt lgkmcnt(0)
	s_add_u32 s48, s56, s4
	v_ashrrev_i32_e32 v3, 31, v2
	s_addc_u32 s49, s57, s5
	s_waitcnt vmcnt(3)
	v_lshlrev_b64 v[34:35], 1, v[2:3]
	v_lshl_add_u64 v[36:37], s[48:49], 0, v[34:35]
	s_lshl_b32 s4, s34, 8
	s_waitcnt vmcnt(2)
	v_add_co_u32_e32 v38, vcc, s33, v36
	s_ashr_i32 s5, s4, 31
	s_nop 0
	v_addc_co_u32_e32 v39, vcc, 0, v37, vcc
	s_lshl_b64 s[4:5], s[4:5], 11
	v_add_co_u32_e32 v40, vcc, s36, v36
	s_add_u32 s50, s29, s4
	s_nop 0
	v_addc_co_u32_e32 v41, vcc, 0, v37, vcc
	s_addc_u32 s51, s30, s5
	s_waitcnt vmcnt(1)
	v_add_co_u32_e32 v42, vcc, s37, v36
	v_lshl_add_u64 v[44:45], s[50:51], 0, v[34:35]
	s_nop 0
	v_addc_co_u32_e32 v43, vcc, 0, v37, vcc
	s_waitcnt vmcnt(0)
; template <int MI, int NI>
; DI void gemm_kloop(const u16* Au, int lda, const u16* Bu, int ldb, int K, f32x4 (&acc)[NI][MI], unsigned char* smem) {
;   int tid_ = threadIdx.x; asm volatile("" : "+v"(tid_));
;   const int tid = tid_, lane = tid & 63, wave = tid >> 6, wm = wave >> 1, wn = wave & 1;
;   const int lr = tid >> 3, lc = tid & 7;
;   const int voa = lr * lda + lc * 8, vob = lr * ldb + lc * 8;
;   constexpr int NB2 = NI / 2;
;   u32x4 ra[MI], rb[NB2];
;   const int nk = K >> 6;
;   const int fsw = (lane & 15) >> 1;
;   const int fro0 = (lane & 15) * 128 + (((lane >> 4) ^ fsw) << 4);
;   const int fro1 = (lane & 15) * 128 + ((((lane >> 4) + 4) ^ fsw) << 4);
;   const int wof = lr * 128 + ((lc ^ ((lr >> 1) & 7)) << 4);
;     ...
;   GLOAD(0);
;   SWRITE(0);
;   if (nk > 1) GLOAD(64);
; DI void phase_ffnup(const Params& p, int layer, unsigned char* smem) {
;     ...
;     zero_acc<4, 8>(acc);
	s_mov_b64 s[88:89], s[48:49]
	s_mov_b64 s[90:91], s[50:51]
	v_lshrrev_b32_e32 v190, 3, v166
	v_lshlrev_b32_e32 v191, 4, v166
	v_xor_b32_e32 v191, v191, v166
	v_and_b32_e32 v191, 0x70, v191
	v_lshl_or_b32 v186, v190, 11, v191
	v_lshrrev_b32_e32 v192, 6, v166
	s_nop 0
	v_readfirstlane_b32 s94, v192
	v_and_b32_e32 v190, 15, v166
	v_bfe_u32 v191, v166, 4, 2
	v_lshrrev_b32_e32 v192, 1, v190
	v_xor_b32_e32 v230, v191, v192
	v_or_b32_e32 v191, 4, v191
	v_xor_b32_e32 v231, v191, v192
	v_lshlrev_b32_e32 v190, 7, v190
	v_lshl_or_b32 v230, v230, 4, v190
	v_lshl_or_b32 v231, v231, 4, v190
	v_lshrrev_b32_e32 v190, 7, v166
	v_bfe_u32 v191, v166, 6, 1
	v_mul_u32_u24_e32 v191, 0x4000, v191
	v_add_u32_e32 v232, v191, v230
	v_add_u32_e32 v233, v191, v231
	v_mul_u32_u24_e32 v190, 0x2000, v190
	v_add_u32_e32 v230, v190, v230
	v_add_u32_e32 v231, v190, v231
	s_lshl_b32 s94, s94, 10
	s_mov_b32 m0, s94
	s_nop 0
	global_load_lds_dwordx4 v186, s[88:89]
	s_add_u32 m0, m0, 0x2000
	s_add_u32 s92, s88, 0x20000
	s_addc_u32 s93, s89, 0
	global_load_lds_dwordx4 v186, s[92:93]
	s_add_u32 m0, m0, 0x2000
	s_add_u32 s92, s88, 0x40000
	s_addc_u32 s93, s89, 0
	global_load_lds_dwordx4 v186, s[92:93]
	s_add_u32 m0, m0, 0x2000
	s_add_u32 s92, s88, 0x60000
	s_addc_u32 s93, s89, 0
	global_load_lds_dwordx4 v186, s[92:93]
	s_add_u32 m0, m0, 0x2000
	s_nop 0
	global_load_lds_dwordx4 v186, s[90:91]
	s_add_u32 m0, m0, 0x2000
	s_add_u32 s92, s90, 0x20000
	s_addc_u32 s93, s91, 0
	global_load_lds_dwordx4 v186, s[92:93]
	s_add_u32 m0, m0, 0x2000
	s_add_u32 s92, s90, 0x40000
	s_addc_u32 s93, s91, 0
	global_load_lds_dwordx4 v186, s[92:93]
	s_add_u32 m0, m0, 0x2000
	s_add_u32 s92, s90, 0x60000
	s_addc_u32 s93, s91, 0
	global_load_lds_dwordx4 v186, s[92:93]
	s_add_u32 s88, s88, 0x80
	s_addc_u32 s89, s89, 0
	s_add_u32 s90, s90, 0x80
	s_addc_u32 s91, s91, 0
	v_add_co_u32_e32 v46, vcc, s33, v44
	s_nop 0
	s_nop 0
	v_addc_co_u32_e32 v47, vcc, 0, v45, vcc
	v_add_co_u32_e32 v48, vcc, s36, v44
	s_nop 0
	s_nop 0
	v_addc_co_u32_e32 v49, vcc, 0, v45, vcc
	v_add_co_u32_e32 v50, vcc, s37, v44
	s_nop 0
	s_nop 0
	v_addc_co_u32_e32 v51, vcc, 0, v45, vcc
	s_nop 0
	s_nop 0
	s_nop 0
	s_nop 0
	s_nop 0
	s_nop 0
	s_nop 0
	s_nop 0
	s_nop 0
	s_nop 0
	s_add_u32 s4, s23, s4
	s_addc_u32 s5, s21, s5
	s_mulk_i32 s52, 0xfe
	v_lshl_add_u64 v[168:169], s[4:5], 0, v[34:35]
	s_mul_i32 s4, s53, 0x3f8
	s_add_i32 s4, s4, s52
	s_mulk_i32 s54, 0x5e
	s_sub_i32 s4, s4, s54
	v_lshlrev_b32_e32 v58, 4, v52
	s_add_i32 s4, s4, -2
	v_and_b32_e32 v54, 15, v52
	v_bfe_u32 v55, v52, 1, 3
	v_lshrrev_b32_e32 v56, 4, v52
	v_bfe_u32 v57, v52, 4, 2
	v_lshlrev_b32_e32 v59, 6, v52
	v_lshlrev_b32_e32 v60, 8, v52
	v_xor_b32_e32 v52, v58, v52
	v_lshlrev_b32_e32 v53, 7, v53
	s_ashr_i32 s5, s4, 31
	v_and_or_b32 v177, v52, s12, v53
	s_lshl_b64 s[4:5], s[4:5], 11
	v_lshlrev_b32_e32 v54, 7, v54
	v_bitop3_b32 v56, v56, v55, 3 bitop3:0x6c
	s_add_u32 s4, s56, s4
	v_lshl_or_b32 v176, v56, 4, v54
	s_addc_u32 s5, s57, s5
	s_mov_b32 s48, 0
	v_and_b32_e32 v174, 0xffffe000, v59
	v_and_b32_e32 v175, 0x4000, v60
	v_lshl_add_u64 v[170:171], s[4:5], 0, v[34:35]
	s_mov_b64 s[4:5], 0
	v_bitop3_b32 v2, v57, v55, 4 bitop3:0x36
	v_lshl_or_b32 v173, v2, 4, v54
	v_mov_b32_e32 v54, 0
	v_mov_b32_e32 v55, v54
	v_mov_b32_e32 v56, v54
	v_mov_b32_e32 v57, v54
	v_mov_b32_e32 v38, v54
	v_mov_b32_e32 v39, v54
	v_mov_b32_e32 v40, v54
	v_mov_b32_e32 v41, v54
	v_mov_b32_e32 v26, v54
	v_mov_b32_e32 v27, v54
	v_mov_b32_e32 v28, v54
	v_mov_b32_e32 v29, v54
	v_mov_b32_e32 v10, v54
	v_mov_b32_e32 v11, v54
	v_mov_b32_e32 v12, v54
	v_mov_b32_e32 v13, v54
	v_mov_b32_e32 v30, v54
	v_mov_b32_e32 v31, v54
	v_mov_b32_e32 v32, v54
	v_mov_b32_e32 v33, v54
	v_mov_b32_e32 v2, v54
	v_mov_b32_e32 v3, v54
	v_mov_b32_e32 v4, v54
	v_mov_b32_e32 v5, v54
	v_mov_b32_e32 v6, v54
	v_mov_b32_e32 v7, v54
	v_mov_b32_e32 v8, v54
	v_mov_b32_e32 v9, v54
	v_mov_b32_e32 v14, v54
	v_mov_b32_e32 v15, v54
	v_mov_b32_e32 v16, v54
	v_mov_b32_e32 v17, v54
	v_mov_b32_e32 v18, v54
	v_mov_b32_e32 v19, v54
	v_mov_b32_e32 v20, v54
	v_mov_b32_e32 v21, v54
	v_mov_b32_e32 v22, v54
	v_mov_b32_e32 v23, v54
	v_mov_b32_e32 v24, v54
	v_mov_b32_e32 v25, v54
	v_mov_b32_e32 v34, v54
	v_mov_b32_e32 v35, v54
	v_mov_b32_e32 v36, v54
	v_mov_b32_e32 v37, v54
	v_mov_b32_e32 v42, v54
	v_mov_b32_e32 v43, v54
	v_mov_b32_e32 v44, v54
	v_mov_b32_e32 v45, v54
	v_mov_b32_e32 v46, v54
	v_mov_b32_e32 v47, v54
	v_mov_b32_e32 v48, v54
	v_mov_b32_e32 v49, v54
	v_mov_b32_e32 v50, v54
	v_mov_b32_e32 v51, v54
	v_mov_b32_e32 v52, v54
	v_mov_b32_e32 v53, v54
	v_mov_b32_e32 v58, v54
	v_mov_b32_e32 v59, v54
	v_mov_b32_e32 v60, v54
	v_mov_b32_e32 v61, v54
	v_mov_b32_e32 v62, v54
	v_mov_b32_e32 v63, v54
	v_mov_b32_e32 v64, v54
	v_mov_b32_e32 v65, v54
	v_mov_b32_e32 v66, v54
	v_mov_b32_e32 v67, v54
	v_mov_b32_e32 v68, v54
	v_mov_b32_e32 v69, v54
	v_mov_b32_e32 v70, v54
	v_mov_b32_e32 v71, v54
	v_mov_b32_e32 v72, v54
	v_mov_b32_e32 v73, v54
	v_mov_b32_e32 v74, v54
	v_mov_b32_e32 v75, v54
	v_mov_b32_e32 v76, v54
	v_mov_b32_e32 v77, v54
	v_mov_b32_e32 v78, v54
	v_mov_b32_e32 v79, v54
	v_mov_b32_e32 v80, v54
	v_mov_b32_e32 v81, v54
	v_mov_b32_e32 v82, v54
	v_mov_b32_e32 v83, v54
	v_mov_b32_e32 v84, v54
	v_mov_b32_e32 v85, v54
	v_mov_b32_e32 v86, v54
	v_mov_b32_e32 v87, v54
	v_mov_b32_e32 v88, v54
	v_mov_b32_e32 v89, v54
	v_mov_b32_e32 v90, v54
	v_mov_b32_e32 v91, v54
	v_mov_b32_e32 v92, v54
	v_mov_b32_e32 v93, v54
	v_mov_b32_e32 v94, v54
	v_mov_b32_e32 v95, v54
	v_mov_b32_e32 v96, v54
	v_mov_b32_e32 v97, v54
	v_mov_b32_e32 v98, v54
	v_mov_b32_e32 v99, v54
	v_mov_b32_e32 v100, v54
	v_mov_b32_e32 v101, v54
	v_mov_b32_e32 v102, v54
	v_mov_b32_e32 v103, v54
	v_mov_b32_e32 v104, v54
	v_mov_b32_e32 v105, v54
	v_mov_b32_e32 v106, v54
	v_mov_b32_e32 v107, v54
	v_mov_b32_e32 v108, v54
	v_mov_b32_e32 v109, v54
	v_mov_b32_e32 v114, v54
	v_mov_b32_e32 v115, v54
	v_mov_b32_e32 v116, v54
	v_mov_b32_e32 v117, v54
	v_mov_b32_e32 v146, v54
	v_mov_b32_e32 v147, v54
	v_mov_b32_e32 v148, v54
	v_mov_b32_e32 v149, v54
	v_mov_b32_e32 v154, v54
	v_mov_b32_e32 v155, v54
	v_mov_b32_e32 v156, v54
	v_mov_b32_e32 v157, v54
	v_mov_b32_e32 v150, v54
	v_mov_b32_e32 v151, v54
	v_mov_b32_e32 v152, v54
	v_mov_b32_e32 v153, v54
	v_mov_b32_e32 v158, v54
	v_mov_b32_e32 v159, v54
	v_mov_b32_e32 v160, v54
	v_mov_b32_e32 v161, v54
	s_mov_b32 s95, 0

; DI void phase_resid(const Params& p, int from_x, const u16* A, int K, const u16* W, float* rowss_next, bool last,
;                     unsigned char* smem) {
;     ...
;   for (int it = vblock(); it < nfull; it += gridDim.x) {
;     const int g = it / (4 * NT), rem = it - g * (4 * NT), nt = rem >> 2, mt = g * 4 + (rem & 3);
;     f32x4 acc[8][4];
;     zero_acc<4, 8>(acc);
;     gemm_kloop<4, 8>(A + (size_t)(mt * 256) * K, K, W + (size_t)(nt * 256) * K, K, K, acc, smem);
.LBB0_72:
	s_ashr_i32 s2, s49, 31
	s_lshr_b32 s2, s2, 28
	s_add_i32 s2, s49, s2
	s_lshl_b32 s2, s2, 6
	s_and_b32 s57, s2, 0xfffffc00
	s_lshl_b32 s2, s49, 8
	s_and_b32 s2, s2, 0x300
	v_mov_b32_e32 v52, v166
	s_or_b32 s34, s57, s2
	s_ashr_i32 s35, s34, 31
	v_lshlrev_b32_e32 v2, 3, v52
	v_ashrrev_i32_e32 v53, 3, v52
	v_and_b32_e32 v2, 56, v2
	s_and_b32 s56, s52, 0x300
	s_lshl_b64 s[2:3], s[34:35], 11
	v_lshl_or_b32 v2, v53, 10, v2
	s_add_u32 s28, s84, s2
	s_waitcnt lgkmcnt(0)
	v_ashrrev_i32_e32 v3, 31, v2
	s_addc_u32 s29, s85, s3
	s_lshl_b32 s2, s49, 6
	s_waitcnt vmcnt(3)
	v_lshlrev_b64 v[34:35], 1, v[2:3]
	s_sub_i32 s2, s2, s57
	v_lshl_add_u64 v[36:37], s[28:29], 0, v[34:35]
	s_and_b32 s2, s2, 0xffffff00
	s_waitcnt vmcnt(2)
	v_add_co_u32_e32 v38, vcc, s33, v36
	s_ashr_i32 s3, s2, 31
	s_nop 0
	v_addc_co_u32_e32 v39, vcc, 0, v37, vcc
	s_lshl_b64 s[54:55], s[2:3], 11
	v_add_co_u32_e32 v40, vcc, s36, v36
	s_add_u32 s54, s30, s54
	s_nop 0
	v_addc_co_u32_e32 v41, vcc, 0, v37, vcc
	s_addc_u32 s55, s31, s55
	s_waitcnt vmcnt(1)
	v_add_co_u32_e32 v42, vcc, s37, v36
	v_lshl_add_u64 v[44:45], s[54:55], 0, v[34:35]
	s_nop 0
	v_addc_co_u32_e32 v43, vcc, 0, v37, vcc
	s_waitcnt vmcnt(0)
; template <int MI, int NI>
; DI void gemm_kloop(const u16* Au, int lda, const u16* Bu, int ldb, int K, f32x4 (&acc)[NI][MI], unsigned char* smem) {
;   int tid_ = threadIdx.x; asm volatile("" : "+v"(tid_));
;   const int tid = tid_, lane = tid & 63, wave = tid >> 6, wm = wave >> 1, wn = wave & 1;
;   const int lr = tid >> 3, lc = tid & 7;
;   const int voa = lr * lda + lc * 8, vob = lr * ldb + lc * 8;
;   constexpr int NB2 = NI / 2;
;   u32x4 ra[MI], rb[NB2];
;   const int nk = K >> 6;
;   const int fsw = (lane & 15) >> 1;
;   const int fro0 = (lane & 15) * 128 + (((lane >> 4) ^ fsw) << 4);
;   const int fro1 = (lane & 15) * 128 + ((((lane >> 4) + 4) ^ fsw) << 4);
;   const int wof = lr * 128 + ((lc ^ ((lr >> 1) & 7)) << 4);
;     ...
;   GLOAD(0);
;   SWRITE(0);
;   if (nk > 1) GLOAD(64);
; DI void phase_resid(const Params& p, int from_x, const u16* A, int K, const u16* W, float* rowss_next, bool last,
;                     unsigned char* smem) {
;     ...
;     zero_acc<4, 8>(acc);
	s_mov_b64 s[88:89], s[28:29]
	s_mov_b64 s[90:91], s[54:55]
	v_lshrrev_b32_e32 v142, 3, v166
	v_lshlrev_b32_e32 v143, 4, v166
	v_xor_b32_e32 v143, v143, v166
	v_and_b32_e32 v143, 0x70, v143
	v_lshl_or_b32 v255, v142, 11, v143
	v_lshrrev_b32_e32 v144, 6, v166
	s_nop 0
	v_readfirstlane_b32 s94, v144
	v_and_b32_e32 v142, 15, v166
	v_bfe_u32 v143, v166, 4, 2
	v_lshrrev_b32_e32 v144, 1, v142
	v_xor_b32_e32 v183, v143, v144
	v_or_b32_e32 v143, 4, v143
	v_xor_b32_e32 v226, v143, v144
	v_lshlrev_b32_e32 v142, 7, v142
	v_lshl_or_b32 v183, v183, 4, v142
	v_lshl_or_b32 v226, v226, 4, v142
	v_lshrrev_b32_e32 v142, 7, v166
	v_bfe_u32 v143, v166, 6, 1
	v_mul_u32_u24_e32 v143, 0x4000, v143
	v_add_u32_e32 v227, v143, v183
	v_add_u32_e32 v254, v143, v226
	v_mul_u32_u24_e32 v142, 0x2000, v142
	v_add_u32_e32 v183, v142, v183
	v_add_u32_e32 v226, v142, v226
	s_lshl_b32 s94, s94, 10
	s_mov_b32 m0, s94
	s_nop 0
	global_load_lds_dwordx4 v255, s[88:89]
	s_add_u32 m0, m0, 0x2000
	s_add_u32 s92, s88, 0x20000
	s_addc_u32 s93, s89, 0
	global_load_lds_dwordx4 v255, s[92:93]
	s_add_u32 m0, m0, 0x2000
	s_add_u32 s92, s88, 0x40000
	s_addc_u32 s93, s89, 0
	global_load_lds_dwordx4 v255, s[92:93]
	s_add_u32 m0, m0, 0x2000
	s_add_u32 s92, s88, 0x60000
	s_addc_u32 s93, s89, 0
	global_load_lds_dwordx4 v255, s[92:93]
	s_add_u32 m0, m0, 0x2000
	s_nop 0
	global_load_lds_dwordx4 v255, s[90:91]
	s_add_u32 m0, m0, 0x2000
	s_add_u32 s92, s90, 0x20000
	s_addc_u32 s93, s91, 0
	global_load_lds_dwordx4 v255, s[92:93]
	s_add_u32 m0, m0, 0x2000
	s_add_u32 s92, s90, 0x40000
	s_addc_u32 s93, s91, 0
	global_load_lds_dwordx4 v255, s[92:93]
	s_add_u32 m0, m0, 0x2000
	s_add_u32 s92, s90, 0x60000
	s_addc_u32 s93, s91, 0
	global_load_lds_dwordx4 v255, s[92:93]
	s_add_u32 s88, s88, 0x80
	s_addc_u32 s89, s89, 0
	s_add_u32 s90, s90, 0x80
	s_addc_u32 s91, s91, 0
	v_add_co_u32_e32 v46, vcc, s33, v44
	s_nop 0
	s_nop 0
	v_addc_co_u32_e32 v47, vcc, 0, v45, vcc
	v_add_co_u32_e32 v48, vcc, s36, v44
	s_nop 0
	s_nop 0
	v_addc_co_u32_e32 v49, vcc, 0, v45, vcc
	v_add_co_u32_e32 v50, vcc, s37, v44
	s_nop 0
	s_nop 0
	v_addc_co_u32_e32 v51, vcc, 0, v45, vcc
	s_nop 0
	s_nop 0
	s_nop 0
	s_nop 0
	s_nop 0
	s_nop 0
	s_nop 0
	s_nop 0
	s_nop 0
	s_nop 0
	s_sub_i32 s28, s50, s57
	s_and_b32 s28, s28, 0xffffff00
	s_ashr_i32 s29, s28, 31
	s_lshl_b64 s[28:29], s[28:29], 11
	s_add_u32 s28, s23, s28
	s_addc_u32 s29, s21, s29
	v_lshl_add_u64 v[168:169], s[28:29], 0, v[34:35]
	s_or_b32 s28, s57, s56
	s_ashr_i32 s29, s28, 31
	v_lshlrev_b32_e32 v58, 4, v52
	s_lshl_b64 s[28:29], s[28:29], 11
	v_and_b32_e32 v54, 15, v52
	v_bfe_u32 v55, v52, 1, 3
	v_lshrrev_b32_e32 v56, 4, v52
	v_bfe_u32 v57, v52, 4, 2
	v_lshlrev_b32_e32 v59, 6, v52
	v_lshlrev_b32_e32 v60, 8, v52
	v_xor_b32_e32 v52, v58, v52
	v_lshlrev_b32_e32 v53, 7, v53
	s_add_u32 s28, s84, s28
	v_lshlrev_b32_e32 v54, 7, v54
	v_bitop3_b32 v56, v56, v55, 3 bitop3:0x6c
	v_bitop3_b32 v55, v57, v55, 4 bitop3:0x36
	v_and_or_b32 v182, v52, s12, v53
	s_addc_u32 s29, s85, s29
	v_mov_b32_e32 v158, 0
	s_mov_b32 s3, 0
	v_and_b32_e32 v179, 0xffffe000, v59
	v_and_b32_e32 v181, 0x4000, v60
	v_lshl_or_b32 v180, v56, 4, v54
	v_lshl_or_b32 v178, v55, 4, v54
	v_lshl_add_u64 v[170:171], s[28:29], 0, v[34:35]
	s_mov_b64 s[28:29], 0
	v_mov_b32_e32 v159, v158
	v_mov_b32_e32 v160, v158
	v_mov_b32_e32 v161, v158
	v_mov_b32_e32 v62, v158
	v_mov_b32_e32 v63, v158
	v_mov_b32_e32 v64, v158
	v_mov_b32_e32 v65, v158
	v_mov_b32_e32 v74, v158
	v_mov_b32_e32 v75, v158
	v_mov_b32_e32 v76, v158
	v_mov_b32_e32 v77, v158
	v_mov_b32_e32 v82, v158
	v_mov_b32_e32 v83, v158
	v_mov_b32_e32 v84, v158
	v_mov_b32_e32 v85, v158
	v_mov_b32_e32 v66, v158
	v_mov_b32_e32 v67, v158
	v_mov_b32_e32 v68, v158
	v_mov_b32_e32 v69, v158
	v_mov_b32_e32 v38, v158
	v_mov_b32_e32 v39, v158
	v_mov_b32_e32 v40, v158
	v_mov_b32_e32 v41, v158
	v_mov_b32_e32 v26, v158
	v_mov_b32_e32 v27, v158
	v_mov_b32_e32 v28, v158
	v_mov_b32_e32 v29, v158
	v_mov_b32_e32 v10, v158
	v_mov_b32_e32 v11, v158
	v_mov_b32_e32 v12, v158
	v_mov_b32_e32 v13, v158
	v_mov_b32_e32 v30, v158
	v_mov_b32_e32 v31, v158
	v_mov_b32_e32 v32, v158
	v_mov_b32_e32 v33, v158
	v_mov_b32_e32 v2, v158
	v_mov_b32_e32 v3, v158
	v_mov_b32_e32 v4, v158
	v_mov_b32_e32 v5, v158
	v_mov_b32_e32 v6, v158
	v_mov_b32_e32 v7, v158
	v_mov_b32_e32 v8, v158
	v_mov_b32_e32 v9, v158
	v_mov_b32_e32 v14, v158
	v_mov_b32_e32 v15, v158
	v_mov_b32_e32 v16, v158
	v_mov_b32_e32 v17, v158
	v_mov_b32_e32 v18, v158
	v_mov_b32_e32 v19, v158
	v_mov_b32_e32 v20, v158
	v_mov_b32_e32 v21, v158
	v_mov_b32_e32 v22, v158
	v_mov_b32_e32 v23, v158
	v_mov_b32_e32 v24, v158
	v_mov_b32_e32 v25, v158
	v_mov_b32_e32 v34, v158
	v_mov_b32_e32 v35, v158
	v_mov_b32_e32 v36, v158
	v_mov_b32_e32 v37, v158
	v_mov_b32_e32 v42, v158
	v_mov_b32_e32 v43, v158
	v_mov_b32_e32 v44, v158
	v_mov_b32_e32 v45, v158
	v_mov_b32_e32 v46, v158
	v_mov_b32_e32 v47, v158
	v_mov_b32_e32 v48, v158
	v_mov_b32_e32 v49, v158
	v_mov_b32_e32 v50, v158
	v_mov_b32_e32 v51, v158
	v_mov_b32_e32 v52, v158
	v_mov_b32_e32 v53, v158
	v_mov_b32_e32 v54, v158
	v_mov_b32_e32 v55, v158
	v_mov_b32_e32 v56, v158
	v_mov_b32_e32 v57, v158
	v_mov_b32_e32 v58, v158
	v_mov_b32_e32 v59, v158
	v_mov_b32_e32 v60, v158
	v_mov_b32_e32 v61, v158
	v_mov_b32_e32 v70, v158
	v_mov_b32_e32 v71, v158
	v_mov_b32_e32 v72, v158
	v_mov_b32_e32 v73, v158
	v_mov_b32_e32 v78, v158
	v_mov_b32_e32 v79, v158
	v_mov_b32_e32 v80, v158
	v_mov_b32_e32 v81, v158
	v_mov_b32_e32 v86, v158
	v_mov_b32_e32 v87, v158
	v_mov_b32_e32 v88, v158
	v_mov_b32_e32 v89, v158
	v_mov_b32_e32 v90, v158
	v_mov_b32_e32 v91, v158
	v_mov_b32_e32 v92, v158
	v_mov_b32_e32 v93, v158
	v_mov_b32_e32 v94, v158
	v_mov_b32_e32 v95, v158
	v_mov_b32_e32 v96, v158
	v_mov_b32_e32 v97, v158
	v_mov_b32_e32 v98, v158
	v_mov_b32_e32 v99, v158
	v_mov_b32_e32 v100, v158
	v_mov_b32_e32 v101, v158
	v_mov_b32_e32 v102, v158
	v_mov_b32_e32 v103, v158
	v_mov_b32_e32 v104, v158
	v_mov_b32_e32 v105, v158
	v_mov_b32_e32 v106, v158
	v_mov_b32_e32 v107, v158
	v_mov_b32_e32 v108, v158
	v_mov_b32_e32 v109, v158
	v_mov_b32_e32 v110, v158
	v_mov_b32_e32 v111, v158
	v_mov_b32_e32 v112, v158
	v_mov_b32_e32 v113, v158
	v_mov_b32_e32 v114, v158
	v_mov_b32_e32 v115, v158
	v_mov_b32_e32 v116, v158
	v_mov_b32_e32 v117, v158
	v_mov_b32_e32 v118, v158
	v_mov_b32_e32 v119, v158
	v_mov_b32_e32 v120, v158
	v_mov_b32_e32 v121, v158
	v_mov_b32_e32 v134, v158
	v_mov_b32_e32 v135, v158
	v_mov_b32_e32 v136, v158
	v_mov_b32_e32 v137, v158
	s_mov_b32 s95, 0

; DI f32x4 mfma16(bf16x8 a, bf16x8 b, f32x4 c) { return __builtin_amdgcn_mfma_f32_16x16x32_bf16(a, b, c, 0, 0, 0); }
; template <int PASS, bool DIAG>
; DI void idx_tile(const bf16x8 kf, const bf16x8 (&qf)[8], const float (&wq)[8], int kt, int lm, int lg, int tq, bool selall, u32 bA, u32 pfx,
;                  u32* hist, u32* maskw, u32* cand, u32* ccnt) {
;   const f32x4 z4 = {0.f, 0.f, 0.f, 0.f};
;   f32x4 sc = z4;
; #pragma unroll
;   for (int j = 0; j < 8; ++j) {
;     f32x4 d = mfma16(kf, qf[j], z4);
; #pragma unroll
;     for (int r = 0; r < 4; ++r) sc[r] += wq[j] * fmaxf(d[r], 0.f);
;   }
;   u32 selbits = 0u;
; #pragma unroll
;   for (int r = 0; r < 4; ++r) {
;     const int key = kt * 16 + lg * 4 + r;
;     const bool valid = !DIAG || key <= tq;
;     const u32 bits = __float_as_uint(sc[r]);
;     const u32 u = bits ^ ((u32)((int)bits >> 31) | 0x80000000u);
;     if (PASS == 0) {
;       if (valid) { const u32 bin = u >> 22; atomicAdd(&hist[lm * 512 + (bin >> 1)], 1u << ((bin & 1) * 16)); }
; template <int PASS>
; DI void idx_pass(const u16* kp, const bf16x8 (&qf)[8], const float (&wq)[8], int wave, int ntile, int lm, int lg, int tq, bool selall,
;                  u32 bA, u32 pfx, u32* hist, u32* maskw, u32* cand, u32* ccnt) {
;   auto ldk = [&](int t) { return *(const bf16x8*)(kp + (size_t)(t < ntile ? t : 0) * 512); };
;   int kt = wave;
;   bf16x8 ka = ldk(kt), kb = ldk(kt + 4);
;   for (; kt + 4 < ntile - 1; kt += 8) {
;     const bf16x8 kc = ldk(kt + 8), kd = ldk(kt + 12);
;     idx_tile<PASS, false>(ka, qf, wq, kt, lm, lg, tq, selall, bA, pfx, hist, maskw, cand, ccnt);
;     idx_tile<PASS, false>(kb, qf, wq, kt + 4, lm, lg, tq, selall, bA, pfx, hist, maskw, cand, ccnt);
;     ka = kc; kb = kd;
.LBB0_396:
	s_waitcnt vmcnt(1)
	v_mov_b64_e32 v[70:71], v[44:45]
	v_mov_b64_e32 v[68:69], v[42:43]
	v_mov_b32_e32 v46, v111
	v_add_u32_e32 v111, 8, v46
	v_cmp_le_i32_e64 s[4:5], v111, v97
	v_add_u32_e32 v110, 12, v46
	v_mfma_f32_16x16x32_bf16 v[72:75], v[68:71], v[38:41], 0
	v_cndmask_b32_e64 v42, 0, v111, s[4:5]
	v_cmp_le_i32_e64 s[4:5], v110, v97
	v_ashrrev_i32_e32 v43, 31, v42
	v_lshlrev_b64 v[42:43], 10, v[42:43]
	v_cndmask_b32_e64 v46, 0, v110, s[4:5]
	s_nop 2
	v_max_f32_e32 v72, 0, v72
	v_fma_f32 v76, v6, v72, 0
	v_max_f32_e32 v72, 0, v73
	v_fma_f32 v77, v6, v72, 0
	v_max_f32_e32 v72, 0, v74
	v_fma_f32 v78, v6, v72, 0
	v_max_f32_e32 v72, 0, v75
	v_fma_f32 v79, v6, v72, 0
	v_mfma_f32_16x16x32_bf16 v[72:75], v[68:71], v[34:37], 0
	v_ashrrev_i32_e32 v47, 31, v46
	v_lshlrev_b64 v[46:47], 10, v[46:47]
	v_lshl_add_u64 v[42:43], v[90:91], 0, v[42:43]
	v_lshl_add_u64 v[46:47], v[90:91], 0, v[46:47]
	global_load_dwordx4 v[42:45], v[42:43], off
	s_nop 2
	v_max_f32_e32 v72, 0, v72
	v_mul_f32_e32 v80, v7, v72
	v_max_f32_e32 v72, 0, v73
	v_mul_f32_e32 v81, v7, v72
	v_max_f32_e32 v72, 0, v74
	v_mul_f32_e32 v82, v7, v72
	v_max_f32_e32 v72, 0, v75
	v_mul_f32_e32 v83, v7, v72
	v_mfma_f32_16x16x32_bf16 v[72:75], v[68:71], v[30:33], 0
	v_add_f32_e64 v76, v76, v80
	v_add_f32_e64 v77, v77, v81
	global_load_dwordx4 v[46:49], v[46:47], off
	v_cmp_ge_i32_e64 s[4:5], v110, v97
	s_or_b64 s[6:7], s[4:5], s[6:7]
	s_nop 2
	v_max_f32_e32 v84, 0, v72
	v_max_f32_e32 v85, 0, v73
	v_max_f32_e32 v98, 0, v74
	v_max_f32_e32 v99, 0, v75
	v_mfma_f32_16x16x32_bf16 v[72:75], v[68:71], v[26:29], 0
	v_fma_f32 v76, v56, v84, v76
	v_fma_f32 v77, v57, v85, v77
	s_nop 5
	v_max_f32_e32 v100, 0, v72
	v_max_f32_e32 v101, 0, v73
	v_max_f32_e32 v102, 0, v74
	v_max_f32_e32 v103, 0, v75
	v_mfma_f32_16x16x32_bf16 v[72:75], v[68:71], v[22:25], 0
	v_fma_f32 v76, v58, v100, v76
	v_fma_f32 v77, v59, v101, v77
	s_nop 5
	v_max_f32_e32 v104, 0, v72
	v_max_f32_e32 v105, 0, v73
	v_max_f32_e32 v106, 0, v74
	v_max_f32_e32 v107, 0, v75
	v_mfma_f32_16x16x32_bf16 v[72:75], v[68:71], v[18:21], 0
	v_fma_f32 v76, v60, v104, v76
	v_fma_f32 v77, v61, v105, v77
	s_nop 5
	v_max_f32_e32 v112, 0, v72
	v_max_f32_e32 v113, 0, v73
	v_max_f32_e32 v114, 0, v74
	v_max_f32_e32 v115, 0, v75
	v_mfma_f32_16x16x32_bf16 v[72:75], v[68:71], v[14:17], 0
	v_fma_f32 v76, v62, v112, v76
	v_fma_f32 v77, v63, v113, v77
	v_mfma_f32_16x16x32_bf16 v[68:71], v[68:71], v[10:13], 0
	s_nop 4
	v_max_f32_e32 v72, 0, v72
	v_max_f32_e32 v73, 0, v73
	s_nop 0
	v_max_f32_e32 v68, 0, v68
	v_max_f32_e32 v69, 0, v69
	v_pk_fma_f32 v[72:73], v[64:65], v[72:73], v[76:77]
	v_pk_fma_f32 v[68:69], v[66:67], v[68:69], v[72:73]
	v_ashrrev_i32_e32 v73, 31, v68
	v_ashrrev_i32_e32 v72, 31, v69
	v_or_b32_e32 v73, 0x80000000, v73
	v_or_b32_e32 v72, 0x80000000, v72
	v_xor_b32_e32 v68, v73, v68
	v_xor_b32_e32 v69, v72, v69
	v_alignbit_b32 v73, v88, v68, 23
	v_lshrrev_b32_e32 v68, 18, v68
	v_alignbit_b32 v72, v55, v69, 23
	v_and_b32_e32 v68, 16, v68
	v_lshrrev_b32_e32 v69, 18, v69
	v_lshl_add_u32 v73, v73, 2, v96
	v_lshlrev_b32_e64 v68, v68, 1
	v_and_b32_e32 v69, 16, v69
	ds_add_u32 v73, v68
	v_lshl_add_u32 v68, v72, 2, v96
	v_lshlrev_b32_e64 v69, v69, 1
	ds_add_u32 v68, v69
	v_pk_add_f32 v[68:69], v[78:79], v[82:83]
	v_max_f32_e32 v74, 0, v74
	v_pk_fma_f32 v[68:69], v[56:57], v[98:99], v[68:69]
	v_max_f32_e32 v75, 0, v75
	v_pk_fma_f32 v[68:69], v[58:59], v[102:103], v[68:69]
	v_pk_fma_f32 v[68:69], v[60:61], v[106:107], v[68:69]
	v_pk_fma_f32 v[68:69], v[62:63], v[114:115], v[68:69]
	v_max_f32_e32 v70, 0, v70
	v_max_f32_e32 v71, 0, v71
	v_pk_fma_f32 v[68:69], v[64:65], v[74:75], v[68:69]
	s_waitcnt vmcnt(2)
	v_mfma_f32_16x16x32_bf16 v[112:115], v[50:53], v[14:17], 0
	v_fma_f32 v68, v66, v70, v68
	v_fma_f32 v69, v67, v71, v69
	v_ashrrev_i32_e32 v71, 31, v68
	v_ashrrev_i32_e32 v70, 31, v69
	v_or_b32_e32 v71, 0x80000000, v71
	v_or_b32_e32 v70, 0x80000000, v70
	v_xor_b32_e32 v68, v71, v68
	v_xor_b32_e32 v69, v70, v69
	v_alignbit_b32 v71, v88, v68, 23
	v_lshrrev_b32_e32 v68, 18, v68
	v_alignbit_b32 v70, v55, v69, 23
	v_and_b32_e32 v68, 16, v68
	v_lshrrev_b32_e32 v69, 18, v69
	v_lshl_add_u32 v71, v71, 2, v96
	v_lshlrev_b32_e64 v68, v68, 1
	v_and_b32_e32 v69, 16, v69
	ds_add_u32 v71, v68
	v_lshl_add_u32 v68, v70, 2, v96
	v_lshlrev_b32_e64 v69, v69, 1
	ds_add_u32 v68, v69
	v_mfma_f32_16x16x32_bf16 v[68:71], v[50:53], v[38:41], 0
	s_nop 7
	v_max_f32_e32 v68, 0, v68
	v_fma_f32 v82, v6, v68, 0
	v_max_f32_e32 v68, 0, v69
	v_fma_f32 v83, v6, v68, 0
	v_max_f32_e32 v68, 0, v70
	v_fma_f32 v74, v6, v68, 0
	v_max_f32_e32 v68, 0, v71
	v_fma_f32 v75, v6, v68, 0
	v_mfma_f32_16x16x32_bf16 v[68:71], v[50:53], v[34:37], 0
	s_nop 7
	v_max_f32_e32 v68, 0, v68
	v_mul_f32_e32 v84, v7, v68
	v_max_f32_e32 v68, 0, v69
	v_mul_f32_e32 v85, v7, v68
	v_max_f32_e32 v68, 0, v70
	v_mul_f32_e32 v78, v7, v68
	v_max_f32_e32 v68, 0, v71
	v_mul_f32_e32 v79, v7, v68
	v_mfma_f32_16x16x32_bf16 v[68:71], v[50:53], v[30:33], 0
	s_nop 7
	v_max_f32_e32 v98, 0, v68
	v_max_f32_e32 v99, 0, v69
	v_max_f32_e32 v80, 0, v70
	v_max_f32_e32 v81, 0, v71
	v_mfma_f32_16x16x32_bf16 v[68:71], v[50:53], v[26:29], 0
	s_nop 7
	v_max_f32_e32 v100, 0, v68
	v_max_f32_e32 v101, 0, v69
	v_max_f32_e32 v76, 0, v70
	v_max_f32_e32 v77, 0, v71
	v_mfma_f32_16x16x32_bf16 v[68:71], v[50:53], v[22:25], 0
	s_nop 7
	v_max_f32_e32 v102, 0, v68
	v_max_f32_e32 v103, 0, v69
	v_max_f32_e32 v68, v70, v70
	v_max_f32_e32 v69, v71, v71
	v_mfma_f32_16x16x32_bf16 v[70:73], v[50:53], v[18:21], 0
	v_max_f32_e32 v68, 0, v68
	v_max_f32_e32 v69, 0, v69
	v_mfma_f32_16x16x32_bf16 v[50:53], v[50:53], v[10:13], 0
	s_nop 4
	v_max_f32_e32 v104, 0, v70
; DI f32x4 mfma16(bf16x8 a, bf16x8 b, f32x4 c) { return __builtin_amdgcn_mfma_f32_16x16x32_bf16(a, b, c, 0, 0, 0); }
; template <int PASS, bool DIAG>
; DI void idx_tile(const bf16x8 kf, const bf16x8 (&qf)[8], const float (&wq)[8], int kt, int lm, int lg, int tq, bool selall, u32 bA, u32 pfx,
;                  u32* hist, u32* maskw, u32* cand, u32* ccnt) {
;   const f32x4 z4 = {0.f, 0.f, 0.f, 0.f};
;   f32x4 sc = z4;
; #pragma unroll
;   for (int j = 0; j < 8; ++j) {
;     f32x4 d = mfma16(kf, qf[j], z4);
; #pragma unroll
;     for (int r = 0; r < 4; ++r) sc[r] += wq[j] * fmaxf(d[r], 0.f);
;   }
;   u32 selbits = 0u;
; #pragma unroll
;   for (int r = 0; r < 4; ++r) {
;     const int key = kt * 16 + lg * 4 + r;
;     const bool valid = !DIAG || key <= tq;
;     const u32 bits = __float_as_uint(sc[r]);
;     const u32 u = bits ^ ((u32)((int)bits >> 31) | 0x80000000u);
;     if (PASS == 0) {
;       if (valid) { const u32 bin = u >> 22; atomicAdd(&hist[lm * 512 + (bin >> 1)], 1u << ((bin & 1) * 16)); }
; template <int PASS>
; DI void idx_pass(const u16* kp, const bf16x8 (&qf)[8], const float (&wq)[8], int wave, int ntile, int lm, int lg, int tq, bool selall,
;                  u32 bA, u32 pfx, u32* hist, u32* maskw, u32* cand, u32* ccnt) {
;     ...
;   if (kt < ntile - 1) { idx_tile<PASS, false>(ka, qf, wq, kt, lm, lg, tq, selall, bA, pfx, hist, maskw, cand, ccnt); kt += 4; ka = kb; }
	v_max_f32_e32 v105, 0, v71
	v_max_f32_e32 v70, v72, v72
	v_max_f32_e32 v72, v112, v112
	v_max_f32_e32 v112, 0, v50
	v_max_f32_e32 v106, 0, v72
	v_max_f32_e32 v72, v113, v113
	v_max_f32_e32 v113, 0, v51
	v_max_f32_e32 v50, v52, v52
	v_max_f32_e32 v51, v53, v53
	v_pk_add_f32 v[52:53], v[82:83], v[84:85]
	v_max_f32_e32 v107, 0, v72
	v_pk_fma_f32 v[52:53], v[56:57], v[98:99], v[52:53]
	v_pk_fma_f32 v[52:53], v[58:59], v[100:101], v[52:53]
	v_max_f32_e32 v70, 0, v70
	v_pk_fma_f32 v[52:53], v[60:61], v[102:103], v[52:53]
	v_max_f32_e32 v71, 0, v73
	v_pk_fma_f32 v[52:53], v[62:63], v[104:105], v[52:53]
	v_pk_fma_f32 v[52:53], v[64:65], v[106:107], v[52:53]
	v_pk_fma_f32 v[52:53], v[66:67], v[112:113], v[52:53]
	v_max_f32_e32 v72, 0, v114
	v_ashrrev_i32_e32 v83, 31, v52
	v_ashrrev_i32_e32 v82, 31, v53
	v_or_b32_e32 v83, 0x80000000, v83
	v_or_b32_e32 v82, 0x80000000, v82
	v_xor_b32_e32 v52, v83, v52
	v_xor_b32_e32 v53, v82, v53
	v_alignbit_b32 v83, v88, v52, 23
	v_lshrrev_b32_e32 v52, 18, v52
	v_alignbit_b32 v82, v55, v53, 23
	v_and_b32_e32 v52, 16, v52
	v_lshrrev_b32_e32 v53, 18, v53
	v_lshl_add_u32 v83, v83, 2, v96
	v_lshlrev_b32_e64 v52, v52, 1
	v_and_b32_e32 v53, 16, v53
	ds_add_u32 v83, v52
	v_lshl_add_u32 v52, v82, 2, v96
	v_lshlrev_b32_e64 v53, v53, 1
	ds_add_u32 v52, v53
	v_pk_add_f32 v[52:53], v[74:75], v[78:79]
	v_max_f32_e32 v73, 0, v115
	v_pk_fma_f32 v[52:53], v[56:57], v[80:81], v[52:53]
	v_max_f32_e32 v50, 0, v50
	v_pk_fma_f32 v[52:53], v[58:59], v[76:77], v[52:53]
	v_max_f32_e32 v51, 0, v51
	v_pk_fma_f32 v[52:53], v[60:61], v[68:69], v[52:53]
	s_nop 0
	v_pk_fma_f32 v[52:53], v[62:63], v[70:71], v[52:53]
	s_nop 0
	v_pk_fma_f32 v[52:53], v[64:65], v[72:73], v[52:53]
	s_nop 0
	v_pk_fma_f32 v[50:51], v[66:67], v[50:51], v[52:53]
	s_nop 0
	v_ashrrev_i32_e32 v53, 31, v50
	v_ashrrev_i32_e32 v52, 31, v51
	v_or_b32_e32 v53, 0x80000000, v53
	v_or_b32_e32 v52, 0x80000000, v52
	v_xor_b32_e32 v50, v53, v50
	v_xor_b32_e32 v51, v52, v51
	v_alignbit_b32 v53, v88, v50, 23
	v_lshrrev_b32_e32 v50, 18, v50
	v_alignbit_b32 v52, v55, v51, 23
	v_and_b32_e32 v50, 16, v50
	v_lshrrev_b32_e32 v51, 18, v51
	v_lshl_add_u32 v53, v53, 2, v96
	v_lshlrev_b32_e64 v50, v50, 1
	v_and_b32_e32 v51, 16, v51
	ds_add_u32 v53, v50
	v_lshl_add_u32 v50, v52, 2, v96
	v_lshlrev_b32_e64 v51, v51, 1
	ds_add_u32 v50, v51
	s_waitcnt vmcnt(0)
	v_mov_b64_e32 v[52:53], v[48:49]
	v_mov_b64_e32 v[50:51], v[46:47]
	s_andn2_b64 exec, exec, s[6:7]
	s_cbranch_execnz .LBB0_396
	s_or_b64 exec, exec, s[6:7]
	v_mov_b64_e32 v[52:53], v[48:49]
	v_mov_b64_e32 v[50:51], v[46:47]
.LBB0_398:
	s_or_b64 exec, exec, s[2:3]
	v_cmp_lt_i32_e64 s[4:5], v111, v97
	s_and_saveexec_b64 s[2:3], s[4:5]
	s_cbranch_execz .LBB0_400
	s_waitcnt vmcnt(1)
	v_mfma_f32_16x16x32_bf16 v[46:49], v[42:45], v[38:41], 0
	v_mov_b32_e32 v111, v110
	s_nop 6
	v_max_f32_e32 v46, 0, v46
	v_fma_f32 v56, v6, v46, 0
	v_max_f32_e32 v46, 0, v48
	v_fma_f32 v58, v6, v46, 0
	v_max_f32_e32 v47, 0, v47
	v_max_f32_e32 v46, 0, v49
	v_fma_f32 v57, v6, v47, 0
	v_fma_f32 v59, v6, v46, 0
	v_mfma_f32_16x16x32_bf16 v[46:49], v[42:45], v[34:37], 0
	s_nop 7
	v_max_f32_e32 v46, 0, v46
	v_mul_f32_e32 v60, v7, v46
	v_max_f32_e32 v46, 0, v47
	v_mul_f32_e32 v61, v7, v46
	v_max_f32_e32 v46, 0, v48
	v_mul_f32_e32 v62, v7, v46
	v_max_f32_e32 v46, 0, v49
	v_mul_f32_e32 v63, v7, v46
	v_mfma_f32_16x16x32_bf16 v[46:49], v[42:45], v[30:33], 0
	v_add_f32_e64 v56, v56, v60
	v_add_f32_e64 v57, v57, v61
	s_nop 5
	v_max_f32_e32 v64, 0, v46
	v_max_f32_e32 v65, 0, v47
	v_max_f32_e32 v66, 0, v48
	v_max_f32_e32 v67, 0, v49
	v_mfma_f32_16x16x32_bf16 v[46:49], v[42:45], v[26:29], 0
	v_fma_f32 v56, v8, v64, v56
	v_fma_f32 v57, v8, v65, v57
	s_nop 5
	v_max_f32_e32 v68, 0, v46
	v_max_f32_e32 v69, 0, v47
	v_max_f32_e32 v70, 0, v48
	v_max_f32_e32 v71, 0, v49
	v_mfma_f32_16x16x32_bf16 v[46:49], v[42:45], v[22:25], 0
	v_fma_f32 v56, v9, v68, v56
	v_fma_f32 v57, v9, v69, v57
	s_nop 5
	v_max_f32_e32 v72, 0, v46
	v_max_f32_e32 v73, 0, v47
	v_max_f32_e32 v74, 0, v48
	v_max_f32_e32 v75, 0, v49
	v_mfma_f32_16x16x32_bf16 v[46:49], v[42:45], v[18:21], 0
	v_fma_f32 v56, v2, v72, v56
	v_fma_f32 v57, v2, v73, v57
	s_nop 5
	v_max_f32_e32 v76, 0, v46
	v_max_f32_e32 v77, 0, v47
	v_max_f32_e32 v78, 0, v48
	v_max_f32_e32 v79, 0, v49
	v_mfma_f32_16x16x32_bf16 v[46:49], v[42:45], v[14:17], 0
	v_fma_f32 v56, v3, v76, v56
	v_fma_f32 v57, v3, v77, v57
	v_mfma_f32_16x16x32_bf16 v[42:45], v[42:45], v[10:13], 0
	s_nop 4
	v_max_f32_e32 v46, 0, v46
	v_max_f32_e32 v47, 0, v47
	s_nop 0
	v_max_f32_e32 v42, 0, v42
	v_max_f32_e32 v43, 0, v43
	v_pk_fma_f32 v[46:47], v[4:5], v[46:47], v[56:57] op_sel_hi:[0,1,1]
	v_pk_fma_f32 v[42:43], v[4:5], v[42:43], v[46:47] op_sel:[1,0,0]
	v_ashrrev_i32_e32 v47, 31, v42
	v_ashrrev_i32_e32 v46, 31, v43
	v_or_b32_e32 v47, 0x80000000, v47
	v_or_b32_e32 v46, 0x80000000, v46
	v_xor_b32_e32 v42, v47, v42
	v_xor_b32_e32 v43, v46, v43
	v_alignbit_b32 v47, v88, v42, 23
	v_lshrrev_b32_e32 v42, 18, v42
	v_alignbit_b32 v46, v88, v43, 23
	v_and_b32_e32 v42, 16, v42
	v_lshrrev_b32_e32 v43, 18, v43
	v_lshl_add_u32 v47, v47, 2, v96
	v_lshlrev_b32_e64 v42, v42, 1
	v_and_b32_e32 v43, 16, v43
	ds_add_u32 v47, v42
	v_lshl_add_u32 v42, v46, 2, v96
	v_lshlrev_b32_e64 v43, v43, 1
	ds_add_u32 v42, v43
	v_pk_add_f32 v[42:43], v[58:59], v[62:63]
	v_pk_fma_f32 v[42:43], v[8:9], v[66:67], v[42:43] op_sel_hi:[0,1,1]
	v_pk_fma_f32 v[42:43], v[8:9], v[70:71], v[42:43] op_sel:[1,0,0]
	v_max_f32_e32 v48, 0, v48
	v_pk_fma_f32 v[42:43], v[2:3], v[74:75], v[42:43] op_sel_hi:[0,1,1]
	v_max_f32_e32 v49, 0, v49
	v_pk_fma_f32 v[42:43], v[2:3], v[78:79], v[42:43] op_sel:[1,0,0]
	v_max_f32_e32 v44, 0, v44
	v_max_f32_e32 v45, 0, v45
	v_pk_fma_f32 v[42:43], v[4:5], v[48:49], v[42:43] op_sel_hi:[0,1,1]
	v_pk_fma_f32 v[42:43], v[4:5], v[44:45], v[42:43] op_sel:[1,0,0]
	s_nop 0
	v_ashrrev_i32_e32 v45, 31, v42
	v_ashrrev_i32_e32 v44, 31, v43
	v_or_b32_e32 v45, 0x80000000, v45
	v_or_b32_e32 v44, 0x80000000, v44
	v_xor_b32_e32 v42, v45, v42
	v_xor_b32_e32 v43, v44, v43
	v_alignbit_b32 v45, v88, v42, 23
	v_lshrrev_b32_e32 v42, 18, v42
	v_alignbit_b32 v44, v88, v43, 23
	v_and_b32_e32 v42, 16, v42
	v_lshrrev_b32_e32 v43, 18, v43
	v_lshl_add_u32 v45, v45, 2, v96
	v_lshlrev_b32_e64 v42, v42, 1
	v_and_b32_e32 v43, 16, v43
	ds_add_u32 v45, v42
	v_lshl_add_u32 v42, v44, 2, v96
	v_lshlrev_b32_e64 v43, v43, 1
	ds_add_u32 v42, v43
	s_waitcnt vmcnt(0)
	v_mov_b64_e32 v[42:43], v[50:51]
	v_mov_b64_e32 v[44:45], v[52:53]
; DI f32x4 mfma16(bf16x8 a, bf16x8 b, f32x4 c) { return __builtin_amdgcn_mfma_f32_16x16x32_bf16(a, b, c, 0, 0, 0); }
; template <int PASS, bool DIAG>
; DI void idx_tile(const bf16x8 kf, const bf16x8 (&qf)[8], const float (&wq)[8], int kt, int lm, int lg, int tq, bool selall, u32 bA, u32 pfx,
;                  u32* hist, u32* maskw, u32* cand, u32* ccnt) {
;   const f32x4 z4 = {0.f, 0.f, 0.f, 0.f};
;   f32x4 sc = z4;
; #pragma unroll
;   for (int j = 0; j < 8; ++j) {
;     f32x4 d = mfma16(kf, qf[j], z4);
; #pragma unroll
;     for (int r = 0; r < 4; ++r) sc[r] += wq[j] * fmaxf(d[r], 0.f);
;   }
;   u32 selbits = 0u;
; #pragma unroll
;   for (int r = 0; r < 4; ++r) {
;     const int key = kt * 16 + lg * 4 + r;
;     const bool valid = !DIAG || key <= tq;
;     const u32 bits = __float_as_uint(sc[r]);
;     const u32 u = bits ^ ((u32)((int)bits >> 31) | 0x80000000u);
;     if (PASS == 0) {
;       if (valid) { const u32 bin = u >> 22; atomicAdd(&hist[lm * 512 + (bin >> 1)], 1u << ((bin & 1) * 16)); }
; template <int PASS>
; DI void idx_pass(const u16* kp, const bf16x8 (&qf)[8], const float (&wq)[8], int wave, int ntile, int lm, int lg, int tq, bool selall,
;                  u32 bA, u32 pfx, u32* hist, u32* maskw, u32* cand, u32* ccnt) {
;     ...
;   if (kt == ntile - 1) idx_tile<PASS, true>(ka, qf, wq, kt, lm, lg, tq, selall, bA, pfx, hist, maskw, cand, ccnt);
.LBB0_400:
	s_or_b64 exec, exec, s[2:3]
	v_cmp_eq_u32_e64 s[4:5], v111, v97
	v_lshlrev_b32_e32 v98, 2, v54
	s_and_saveexec_b64 s[2:3], s[4:5]
	s_cbranch_execz .LBB0_409
	s_waitcnt vmcnt(1)
	v_mfma_f32_16x16x32_bf16 v[70:73], v[42:45], v[38:41], 0
	v_cmp_le_u32_e64 s[4:5], v98, v88
	v_mfma_f32_16x16x32_bf16 v[66:69], v[42:45], v[34:37], 0
	v_mfma_f32_16x16x32_bf16 v[62:65], v[42:45], v[30:33], 0
	v_mfma_f32_16x16x32_bf16 v[58:61], v[42:45], v[26:29], 0
	v_mfma_f32_16x16x32_bf16 v[54:57], v[42:45], v[22:25], 0
	s_waitcnt vmcnt(0)
	v_mfma_f32_16x16x32_bf16 v[50:53], v[42:45], v[18:21], 0
	v_mfma_f32_16x16x32_bf16 v[46:49], v[42:45], v[14:17], 0
	v_mfma_f32_16x16x32_bf16 v[42:45], v[42:45], v[10:13], 0
	s_and_saveexec_b64 s[6:7], s[4:5]
	s_cbranch_execz .LBB0_403
	v_max_f32_e32 v70, 0, v70
	v_fma_f32 v70, v6, v70, 0
	v_max_f32_e32 v66, 0, v66
	v_fmac_f32_e32 v70, v7, v66
	v_max_f32_e32 v62, 0, v62
	v_fmac_f32_e32 v70, v8, v62
	v_max_f32_e32 v58, 0, v58
	v_fmac_f32_e32 v70, v9, v58
	v_max_f32_e32 v54, 0, v54
	v_fmac_f32_e32 v70, v2, v54
	v_max_f32_e32 v50, 0, v50
	v_fmac_f32_e32 v70, v3, v50
	v_max_f32_e32 v46, 0, v46
	v_fmac_f32_e32 v70, v4, v46
	v_max_f32_e32 v42, 0, v42
	v_fmac_f32_e32 v70, v5, v42
	v_ashrrev_i32_e32 v42, 31, v70
	v_bitop3_b32 v42, v42, v70, s39 bitop3:0x36
	v_alignbit_b32 v46, v88, v42, 23
	v_lshrrev_b32_e32 v42, 18, v42
	v_and_b32_e32 v42, 16, v42
	v_lshl_add_u32 v46, v46, 2, v96
	v_lshlrev_b32_e64 v42, v42, 1
	ds_add_u32 v46, v42
.LBB0_403:
	s_or_b64 exec, exec, s[6:7]
	v_cmp_lt_u32_e64 s[4:5], v98, v88
	s_and_saveexec_b64 s[6:7], s[4:5]
	s_cbranch_execz .LBB0_405
	s_nop 1
	v_max_f32_e32 v42, 0, v71
	v_fma_f32 v42, v6, v42, 0
	v_max_f32_e32 v46, 0, v67
	v_fmac_f32_e32 v42, v7, v46
	v_max_f32_e32 v46, 0, v63
	v_fmac_f32_e32 v42, v8, v46
	v_max_f32_e32 v46, 0, v59
	v_fmac_f32_e32 v42, v9, v46
	v_max_f32_e32 v46, 0, v55
	v_fmac_f32_e32 v42, v2, v46
	v_max_f32_e32 v46, 0, v51
	v_fmac_f32_e32 v42, v3, v46
	v_max_f32_e32 v46, 0, v47
	v_fmac_f32_e32 v42, v4, v46
	v_max_f32_e32 v43, 0, v43
	v_fmac_f32_e32 v42, v5, v43
	v_ashrrev_i32_e32 v43, 31, v42
	v_bitop3_b32 v42, v43, v42, s39 bitop3:0x36
	v_alignbit_b32 v43, v88, v42, 23
	v_lshrrev_b32_e32 v42, 18, v42
	v_and_b32_e32 v42, 16, v42
	v_lshl_add_u32 v43, v43, 2, v96
	v_lshlrev_b32_e64 v42, v42, 1
	ds_add_u32 v43, v42
.LBB0_405:
	s_or_b64 exec, exec, s[6:7]
	s_nop 0
	v_or_b32_e32 v42, v98, v87
	v_or_b32_e32 v43, 2, v42
	v_cmp_le_u32_e64 s[4:5], v43, v108
	s_and_saveexec_b64 s[6:7], s[4:5]
	s_cbranch_execz .LBB0_407
	v_max_f32_e32 v43, 0, v72
	v_fma_f32 v43, v6, v43, 0
	v_max_f32_e32 v46, 0, v68
	v_fmac_f32_e32 v43, v7, v46
	v_max_f32_e32 v46, 0, v64
	v_fmac_f32_e32 v43, v8, v46
	v_max_f32_e32 v46, 0, v60
	v_fmac_f32_e32 v43, v9, v46
	v_max_f32_e32 v46, 0, v56
	v_fmac_f32_e32 v43, v2, v46
	v_max_f32_e32 v46, 0, v52
	v_fmac_f32_e32 v43, v3, v46
	v_max_f32_e32 v46, 0, v48
	v_fmac_f32_e32 v43, v4, v46
	v_max_f32_e32 v44, 0, v44
	v_fmac_f32_e32 v43, v5, v44
	v_ashrrev_i32_e32 v44, 31, v43
	v_bitop3_b32 v43, v44, v43, s39 bitop3:0x36
	v_alignbit_b32 v44, v88, v43, 23
	v_lshrrev_b32_e32 v43, 18, v43
	v_and_b32_e32 v43, 16, v43
	v_lshl_add_u32 v44, v44, 2, v96
	v_lshlrev_b32_e64 v43, v43, 1
	ds_add_u32 v44, v43
.LBB0_407:
	s_or_b64 exec, exec, s[6:7]
	v_or_b32_e32 v42, 3, v42
	v_cmp_le_u32_e64 s[4:5], v42, v108
	s_and_b64 exec, exec, s[4:5]
	s_cbranch_execz .LBB0_409
	v_max_f32_e32 v42, 0, v73
	v_fma_f32 v42, v6, v42, 0
	v_max_f32_e32 v43, 0, v69
	v_fmac_f32_e32 v42, v7, v43
	v_max_f32_e32 v43, 0, v65
	v_fmac_f32_e32 v42, v8, v43
	v_max_f32_e32 v43, 0, v61
	v_fmac_f32_e32 v42, v9, v43
	v_max_f32_e32 v43, 0, v57
	v_fmac_f32_e32 v42, v2, v43
	v_max_f32_e32 v43, 0, v53
	v_fmac_f32_e32 v42, v3, v43
	v_max_f32_e32 v43, 0, v49
	v_fmac_f32_e32 v42, v4, v43
	v_max_f32_e32 v43, 0, v45
	v_fmac_f32_e32 v42, v5, v43
	v_ashrrev_i32_e32 v43, 31, v42
	v_bitop3_b32 v42, v43, v42, s39 bitop3:0x36
	v_alignbit_b32 v43, v88, v42, 23
	v_lshrrev_b32_e32 v42, 18, v42
	v_and_b32_e32 v42, 16, v42
	v_lshl_add_u32 v43, v43, 2, v96
	v_lshlrev_b32_e64 v42, v42, 1
	ds_add_u32 v43, v42

; DI f32x4 mfma16(bf16x8 a, bf16x8 b, f32x4 c) { return __builtin_amdgcn_mfma_f32_16x16x32_bf16(a, b, c, 0, 0, 0); }
; template <int PASS, bool DIAG>
; DI void idx_tile(const bf16x8 kf, const bf16x8 (&qf)[8], const float (&wq)[8], int kt, int lm, int lg, int tq, bool selall, u32 bA, u32 pfx,
;                  u32* hist, u32* maskw, u32* cand, u32* ccnt) {
;   const f32x4 z4 = {0.f, 0.f, 0.f, 0.f};
;   f32x4 sc = z4;
; #pragma unroll
;   for (int j = 0; j < 8; ++j) {
;     f32x4 d = mfma16(kf, qf[j], z4);
; #pragma unroll
;     for (int r = 0; r < 4; ++r) sc[r] += wq[j] * fmaxf(d[r], 0.f);
;   }
;   u32 selbits = 0u;
; #pragma unroll
;   for (int r = 0; r < 4; ++r) {
;     const int key = kt * 16 + lg * 4 + r;
;     const bool valid = !DIAG || key <= tq;
;     const u32 bits = __float_as_uint(sc[r]);
;     const u32 u = bits ^ ((u32)((int)bits >> 31) | 0x80000000u);
;     if (PASS == 0) {
;       if (valid) { const u32 bin = u >> 22; atomicAdd(&hist[lm * 512 + (bin >> 1)], 1u << ((bin & 1) * 16)); }
;     } else if (PASS == 1) {
;       if (valid && (u >> 22) == bA) { const u32 bin = (u >> 12) & 1023u; atomicAdd(&hist[lm * 512 + (bin >> 1)], 1u << ((bin & 1) * 16)); }
; template <int PASS>
; DI void idx_pass(const u16* kp, const bf16x8 (&qf)[8], const float (&wq)[8], int wave, int ntile, int lm, int lg, int tq, bool selall,
;                  u32 bA, u32 pfx, u32* hist, u32* maskw, u32* cand, u32* ccnt) {
;     ...
;   for (; kt + 4 < ntile - 1; kt += 8) {
;     const bf16x8 kc = ldk(kt + 8), kd = ldk(kt + 12);
;     idx_tile<PASS, false>(ka, qf, wq, kt, lm, lg, tq, selall, bA, pfx, hist, maskw, cand, ccnt);
;     idx_tile<PASS, false>(kb, qf, wq, kt + 4, lm, lg, tq, selall, bA, pfx, hist, maskw, cand, ccnt);
;     ka = kc; kb = kd;
.LBB0_605:
	s_waitcnt vmcnt(1)
	v_mov_b64_e32 v[84:85], v[44:45]
	v_mov_b64_e32 v[82:83], v[42:43]
	v_mov_b32_e32 v44, v153
	v_add_u32_e32 v153, 8, v44
	v_cmp_le_i32_e64 s[4:5], v153, v97
	v_add_u32_e32 v44, 12, v44
	v_mfma_f32_16x16x32_bf16 v[54:57], v[82:85], v[38:41], 0
	v_cndmask_b32_e64 v42, 0, v153, s[4:5]
	v_cmp_le_i32_e64 s[4:5], v44, v97
	v_ashrrev_i32_e32 v43, 31, v42
	v_lshlrev_b64 v[42:43], 10, v[42:43]
	v_cndmask_b32_e64 v44, 0, v44, s[4:5]
	v_ashrrev_i32_e32 v45, 31, v44
	v_lshlrev_b64 v[44:45], 10, v[44:45]
	v_lshl_add_u64 v[42:43], v[90:91], 0, v[42:43]
	v_lshl_add_u64 v[50:51], v[90:91], 0, v[44:45]
	global_load_dwordx4 v[42:45], v[42:43], off
	s_nop 0
	global_load_dwordx4 v[50:53], v[50:51], off
	v_mfma_f32_16x16x32_bf16 v[58:61], v[82:85], v[34:37], 0
	v_max_f32_e32 v62, 0, v54
	s_nop 5
	s_nop 0
	v_max_f32_e32 v63, 0, v58
	v_pk_mul_f32 v[66:67], v[6:7], v[62:63]
	v_mfma_f32_16x16x32_bf16 v[62:65], v[82:85], v[30:33], 0
	v_add_f32_e32 v54, 0, v66
	v_add_f32_e32 v54, v54, v67
	v_mfma_f32_16x16x32_bf16 v[66:69], v[82:85], v[26:29], 0
	s_nop 4
	v_max_f32_e32 v70, 0, v62
	s_nop 0
	s_nop 0
	v_max_f32_e32 v71, 0, v66
	v_pk_mul_f32 v[74:75], v[8:9], v[70:71]
	v_mfma_f32_16x16x32_bf16 v[70:73], v[82:85], v[22:25], 0
	v_add_f32_e32 v54, v54, v74
	v_add_f32_e32 v54, v54, v75
	v_mfma_f32_16x16x32_bf16 v[74:77], v[82:85], v[18:21], 0
	s_nop 4
	v_max_f32_e32 v78, 0, v70
	s_nop 0
	s_nop 0
	v_max_f32_e32 v79, 0, v74
	v_pk_mul_f32 v[156:157], v[2:3], v[78:79]
	v_mfma_f32_16x16x32_bf16 v[78:81], v[82:85], v[14:17], 0
	v_add_f32_e32 v54, v54, v156
	v_add_f32_e32 v54, v54, v157
	v_mfma_f32_16x16x32_bf16 v[82:85], v[82:85], v[10:13], 0
	s_nop 4
	v_max_f32_e32 v156, 0, v78
	s_nop 0
	s_nop 0
	v_max_f32_e32 v157, 0, v82
	v_pk_mul_f32 v[156:157], v[4:5], v[156:157]
	s_nop 0
	v_add_f32_e32 v54, v54, v156
	v_add_f32_e32 v54, v54, v157
	v_ashrrev_i32_e32 v58, 31, v54
	v_bitop3_b32 v54, v58, v54, s39 bitop3:0x36
	v_lshrrev_b32_e32 v58, 22, v54
	s_waitcnt lgkmcnt(0)
	v_cmp_eq_u32_e64 s[4:5], v58, v137
	s_and_saveexec_b64 s[8:9], s[4:5]
	s_cbranch_execz .LBB0_607
	v_lshrrev_b32_e32 v58, 8, v54
	v_lshrrev_b32_e32 v54, 11, v54
	v_and_b32_e32 v58, 16, v58
	v_and_b32_e32 v54, 0x7fc, v54
	v_lshlrev_b32_e64 v58, v58, 1
	v_add_u32_e32 v54, v154, v54
	ds_add_u32 v54, v58
.LBB0_607:
	s_or_b64 exec, exec, s[8:9]
	v_max_f32_e32 v54, 0, v55
	v_fma_f32 v54, v6, v54, 0
	v_max_f32_e32 v55, 0, v59
	v_fmac_f32_e32 v54, v7, v55
	v_max_f32_e32 v55, 0, v63
	v_fmac_f32_e32 v54, v8, v55
	v_max_f32_e32 v55, 0, v67
	v_fmac_f32_e32 v54, v9, v55
	v_max_f32_e32 v55, 0, v71
	v_fmac_f32_e32 v54, v2, v55
	v_max_f32_e32 v55, 0, v75
	v_fmac_f32_e32 v54, v3, v55
	v_max_f32_e32 v55, 0, v79
	v_fmac_f32_e32 v54, v4, v55
	v_max_f32_e32 v55, 0, v83
	v_fmac_f32_e32 v54, v5, v55
	v_ashrrev_i32_e32 v55, 31, v54
	v_bitop3_b32 v54, v55, v54, s39 bitop3:0x36
	v_lshrrev_b32_e32 v55, 22, v54
	v_cmp_eq_u32_e64 s[4:5], v55, v137
	s_and_saveexec_b64 s[8:9], s[4:5]
	s_cbranch_execz .LBB0_609
	v_lshrrev_b32_e32 v55, 8, v54
	v_lshrrev_b32_e32 v54, 11, v54
	v_and_b32_e32 v55, 16, v55
	v_and_b32_e32 v54, 0x7fc, v54
	v_lshlrev_b32_e64 v55, v55, 1
	v_add_u32_e32 v54, v154, v54
	ds_add_u32 v54, v55
.LBB0_609:
	s_or_b64 exec, exec, s[8:9]
	v_max_f32_e32 v54, 0, v56
	v_fma_f32 v54, v6, v54, 0
	v_max_f32_e32 v55, 0, v60
	v_fmac_f32_e32 v54, v7, v55
	v_max_f32_e32 v55, 0, v64
	v_fmac_f32_e32 v54, v8, v55
	v_max_f32_e32 v55, 0, v68
	v_fmac_f32_e32 v54, v9, v55
	v_max_f32_e32 v55, 0, v72
	v_fmac_f32_e32 v54, v2, v55
	v_max_f32_e32 v55, 0, v76
	v_fmac_f32_e32 v54, v3, v55
	v_max_f32_e32 v55, 0, v80
	v_fmac_f32_e32 v54, v4, v55
	v_max_f32_e32 v55, 0, v84
	v_fmac_f32_e32 v54, v5, v55
	v_ashrrev_i32_e32 v55, 31, v54
	v_bitop3_b32 v54, v55, v54, s39 bitop3:0x36
	v_lshrrev_b32_e32 v55, 22, v54
	v_cmp_eq_u32_e64 s[4:5], v55, v137
	s_and_saveexec_b64 s[8:9], s[4:5]
	s_cbranch_execz .LBB0_611
	v_lshrrev_b32_e32 v55, 8, v54
	v_lshrrev_b32_e32 v54, 11, v54
	v_and_b32_e32 v55, 16, v55
	v_and_b32_e32 v54, 0x7fc, v54
	v_lshlrev_b32_e64 v55, v55, 1
	v_add_u32_e32 v54, v154, v54
	ds_add_u32 v54, v55
.LBB0_611:
	s_or_b64 exec, exec, s[8:9]
	v_max_f32_e32 v54, 0, v57
	v_fma_f32 v54, v6, v54, 0
	v_max_f32_e32 v55, 0, v61
	v_fmac_f32_e32 v54, v7, v55
	v_max_f32_e32 v55, 0, v65
	v_fmac_f32_e32 v54, v8, v55
	v_max_f32_e32 v55, 0, v69
	v_fmac_f32_e32 v54, v9, v55
	v_max_f32_e32 v55, 0, v73
	v_fmac_f32_e32 v54, v2, v55
	v_max_f32_e32 v55, 0, v77
	v_fmac_f32_e32 v54, v3, v55
	v_max_f32_e32 v55, 0, v81
	v_fmac_f32_e32 v54, v4, v55
	v_max_f32_e32 v55, 0, v85
	v_fmac_f32_e32 v54, v5, v55
	v_ashrrev_i32_e32 v55, 31, v54
	v_bitop3_b32 v54, v55, v54, s39 bitop3:0x36
	v_lshrrev_b32_e32 v55, 22, v54
	v_cmp_eq_u32_e64 s[4:5], v55, v137
	s_and_saveexec_b64 s[8:9], s[4:5]
	s_cbranch_execz .LBB0_613
	v_lshrrev_b32_e32 v55, 8, v54
	v_lshrrev_b32_e32 v54, 11, v54
	v_and_b32_e32 v55, 16, v55
	v_and_b32_e32 v54, 0x7fc, v54
	v_lshlrev_b32_e64 v55, v55, 1
	v_add_u32_e32 v54, v154, v54
	ds_add_u32 v54, v55
; DI f32x4 mfma16(bf16x8 a, bf16x8 b, f32x4 c) { return __builtin_amdgcn_mfma_f32_16x16x32_bf16(a, b, c, 0, 0, 0); }
; template <int PASS, bool DIAG>
; DI void idx_tile(const bf16x8 kf, const bf16x8 (&qf)[8], const float (&wq)[8], int kt, int lm, int lg, int tq, bool selall, u32 bA, u32 pfx,
;                  u32* hist, u32* maskw, u32* cand, u32* ccnt) {
;   const f32x4 z4 = {0.f, 0.f, 0.f, 0.f};
;   f32x4 sc = z4;
; #pragma unroll
;   for (int j = 0; j < 8; ++j) {
;     f32x4 d = mfma16(kf, qf[j], z4);
; #pragma unroll
;     for (int r = 0; r < 4; ++r) sc[r] += wq[j] * fmaxf(d[r], 0.f);
;   }
;   u32 selbits = 0u;
; #pragma unroll
;   for (int r = 0; r < 4; ++r) {
;     const int key = kt * 16 + lg * 4 + r;
;     const bool valid = !DIAG || key <= tq;
;     const u32 bits = __float_as_uint(sc[r]);
;     const u32 u = bits ^ ((u32)((int)bits >> 31) | 0x80000000u);
;     if (PASS == 0) {
;       if (valid) { const u32 bin = u >> 22; atomicAdd(&hist[lm * 512 + (bin >> 1)], 1u << ((bin & 1) * 16)); }
;     } else if (PASS == 1) {
;       if (valid && (u >> 22) == bA) { const u32 bin = (u >> 12) & 1023u; atomicAdd(&hist[lm * 512 + (bin >> 1)], 1u << ((bin & 1) * 16)); }
; template <int PASS>
; DI void idx_pass(const u16* kp, const bf16x8 (&qf)[8], const float (&wq)[8], int wave, int ntile, int lm, int lg, int tq, bool selall,
;                  u32 bA, u32 pfx, u32* hist, u32* maskw, u32* cand, u32* ccnt) {
;     ...
;   for (; kt + 4 < ntile - 1; kt += 8) {
;     const bf16x8 kc = ldk(kt + 8), kd = ldk(kt + 12);
;     idx_tile<PASS, false>(ka, qf, wq, kt, lm, lg, tq, selall, bA, pfx, hist, maskw, cand, ccnt);
;     idx_tile<PASS, false>(kb, qf, wq, kt + 4, lm, lg, tq, selall, bA, pfx, hist, maskw, cand, ccnt);
;     ka = kc; kb = kd;
.LBB0_613:
	s_or_b64 exec, exec, s[8:9]
	s_waitcnt vmcnt(2)
	v_mfma_f32_16x16x32_bf16 v[54:57], v[46:49], v[38:41], 0
	v_mfma_f32_16x16x32_bf16 v[58:61], v[46:49], v[34:37], 0
	s_nop 6
	v_max_f32_e32 v62, 0, v54
	v_max_f32_e32 v63, 0, v58
	v_pk_mul_f32 v[66:67], v[6:7], v[62:63]
	v_mfma_f32_16x16x32_bf16 v[62:65], v[46:49], v[30:33], 0
	v_add_f32_e32 v54, 0, v66
	v_add_f32_e32 v54, v54, v67
	v_mfma_f32_16x16x32_bf16 v[66:69], v[46:49], v[26:29], 0
	s_nop 4
	v_max_f32_e32 v70, 0, v62
	s_nop 0
	s_nop 0
	v_max_f32_e32 v71, 0, v66
	v_pk_mul_f32 v[74:75], v[8:9], v[70:71]
	v_mfma_f32_16x16x32_bf16 v[70:73], v[46:49], v[22:25], 0
	v_add_f32_e32 v54, v54, v74
	v_add_f32_e32 v54, v54, v75
	v_mfma_f32_16x16x32_bf16 v[74:77], v[46:49], v[18:21], 0
	s_nop 4
	v_max_f32_e32 v78, 0, v70
	s_nop 0
	s_nop 0
	v_max_f32_e32 v79, 0, v74
	v_pk_mul_f32 v[82:83], v[2:3], v[78:79]
	v_mfma_f32_16x16x32_bf16 v[78:81], v[46:49], v[14:17], 0
	v_add_f32_e32 v54, v54, v82
	v_add_f32_e32 v54, v54, v83
	v_mfma_f32_16x16x32_bf16 v[46:49], v[46:49], v[10:13], 0
	s_nop 4
	v_max_f32_e32 v58, v78, v78
	s_nop 1
	v_max_f32_e32 v82, 0, v58
	v_max_f32_e32 v83, 0, v46
	v_pk_mul_f32 v[82:83], v[4:5], v[82:83]
	s_nop 0
	v_add_f32_e32 v46, v54, v82
	v_add_f32_e32 v46, v46, v83
	v_ashrrev_i32_e32 v54, 31, v46
	v_bitop3_b32 v46, v54, v46, s39 bitop3:0x36
	v_lshrrev_b32_e32 v54, 22, v46
	v_cmp_eq_u32_e64 s[4:5], v54, v137
	s_and_saveexec_b64 s[8:9], s[4:5]
	s_cbranch_execz .LBB0_615
	v_lshrrev_b32_e32 v54, 8, v46
	v_lshrrev_b32_e32 v46, 11, v46
	v_and_b32_e32 v54, 16, v54
	v_and_b32_e32 v46, 0x7fc, v46
	v_lshlrev_b32_e64 v54, v54, 1
	v_add_u32_e32 v46, v154, v46
	ds_add_u32 v46, v54
.LBB0_615:
	s_or_b64 exec, exec, s[8:9]
	v_max_f32_e32 v46, 0, v55
	v_fma_f32 v46, v6, v46, 0
	v_max_f32_e32 v54, 0, v59
	v_fmac_f32_e32 v46, v7, v54
	v_max_f32_e32 v54, 0, v63
	v_fmac_f32_e32 v46, v8, v54
	v_max_f32_e32 v54, 0, v67
	v_fmac_f32_e32 v46, v9, v54
	v_max_f32_e32 v54, 0, v71
	v_fmac_f32_e32 v46, v2, v54
	v_max_f32_e32 v54, 0, v75
	v_fmac_f32_e32 v46, v3, v54
	v_max_f32_e32 v54, 0, v79
	v_fmac_f32_e32 v46, v4, v54
	v_max_f32_e32 v47, 0, v47
	v_fmac_f32_e32 v46, v5, v47
	v_ashrrev_i32_e32 v47, 31, v46
	v_bitop3_b32 v46, v47, v46, s39 bitop3:0x36
	v_lshrrev_b32_e32 v47, 22, v46
	v_cmp_eq_u32_e64 s[4:5], v47, v137
	s_and_saveexec_b64 s[8:9], s[4:5]
	s_cbranch_execz .LBB0_617
	v_lshrrev_b32_e32 v47, 8, v46
	v_lshrrev_b32_e32 v46, 11, v46
	v_and_b32_e32 v47, 16, v47
	v_and_b32_e32 v46, 0x7fc, v46
	v_lshlrev_b32_e64 v47, v47, 1
	v_add_u32_e32 v46, v154, v46
	ds_add_u32 v46, v47
.LBB0_617:
	s_or_b64 exec, exec, s[8:9]
	v_max_f32_e32 v46, 0, v56
	v_fma_f32 v46, v6, v46, 0
	v_max_f32_e32 v47, 0, v60
	v_fmac_f32_e32 v46, v7, v47
	v_max_f32_e32 v47, 0, v64
	v_fmac_f32_e32 v46, v8, v47
	v_max_f32_e32 v47, 0, v68
	v_fmac_f32_e32 v46, v9, v47
	v_max_f32_e32 v47, 0, v72
	v_fmac_f32_e32 v46, v2, v47
	v_max_f32_e32 v47, 0, v76
	v_fmac_f32_e32 v46, v3, v47
	v_max_f32_e32 v47, 0, v80
	v_fmac_f32_e32 v46, v4, v47
	v_max_f32_e32 v47, 0, v48
	v_fmac_f32_e32 v46, v5, v47
	v_ashrrev_i32_e32 v47, 31, v46
	v_bitop3_b32 v46, v47, v46, s39 bitop3:0x36
	v_lshrrev_b32_e32 v47, 22, v46
	v_cmp_eq_u32_e64 s[4:5], v47, v137
	s_and_saveexec_b64 s[8:9], s[4:5]
	s_cbranch_execz .LBB0_619
	v_lshrrev_b32_e32 v47, 8, v46
	v_lshrrev_b32_e32 v46, 11, v46
	v_and_b32_e32 v47, 16, v47
	v_and_b32_e32 v46, 0x7fc, v46
	v_lshlrev_b32_e64 v47, v47, 1
	v_add_u32_e32 v46, v154, v46
	ds_add_u32 v46, v47
.LBB0_619:
	s_or_b64 exec, exec, s[8:9]
	v_max_f32_e32 v46, 0, v57
	v_fma_f32 v46, v6, v46, 0
	v_max_f32_e32 v47, 0, v61
	v_fmac_f32_e32 v46, v7, v47
	v_max_f32_e32 v47, 0, v65
	v_fmac_f32_e32 v46, v8, v47
	v_max_f32_e32 v47, 0, v69
	v_fmac_f32_e32 v46, v9, v47
	v_max_f32_e32 v47, 0, v73
	v_fmac_f32_e32 v46, v2, v47
	v_max_f32_e32 v47, 0, v77
	v_fmac_f32_e32 v46, v3, v47
	v_max_f32_e32 v47, 0, v81
	v_fmac_f32_e32 v46, v4, v47
	v_max_f32_e32 v47, 0, v49
	v_fmac_f32_e32 v46, v5, v47
	v_ashrrev_i32_e32 v47, 31, v46
	v_bitop3_b32 v46, v47, v46, s39 bitop3:0x36
	v_lshrrev_b32_e32 v47, 22, v46
	v_cmp_eq_u32_e64 s[4:5], v47, v137
	s_and_saveexec_b64 s[8:9], s[4:5]
	s_cbranch_execz .LBB0_604
	v_lshrrev_b32_e32 v47, 8, v46
	v_lshrrev_b32_e32 v46, 11, v46
	v_and_b32_e32 v47, 16, v47
	v_and_b32_e32 v46, 0x7fc, v46
	v_lshlrev_b32_e64 v47, v47, 1
	v_add_u32_e32 v46, v154, v46
	ds_add_u32 v46, v47
	s_branch .LBB0_604

; DI f32x4 mfma16(bf16x8 a, bf16x8 b, f32x4 c) { return __builtin_amdgcn_mfma_f32_16x16x32_bf16(a, b, c, 0, 0, 0); }
; template <int PASS, bool DIAG>
; DI void idx_tile(const bf16x8 kf, const bf16x8 (&qf)[8], const float (&wq)[8], int kt, int lm, int lg, int tq, bool selall, u32 bA, u32 pfx,
;                  u32* hist, u32* maskw, u32* cand, u32* ccnt) {
;   const f32x4 z4 = {0.f, 0.f, 0.f, 0.f};
;   f32x4 sc = z4;
; #pragma unroll
;   for (int j = 0; j < 8; ++j) {
;     f32x4 d = mfma16(kf, qf[j], z4);
; #pragma unroll
;     for (int r = 0; r < 4; ++r) sc[r] += wq[j] * fmaxf(d[r], 0.f);
;   }
;   u32 selbits = 0u;
; #pragma unroll
;   for (int r = 0; r < 4; ++r) {
;     const int key = kt * 16 + lg * 4 + r;
;     const bool valid = !DIAG || key <= tq;
;     const u32 bits = __float_as_uint(sc[r]);
;     const u32 u = bits ^ ((u32)((int)bits >> 31) | 0x80000000u);
;     if (PASS == 0) {
;       if (valid) { const u32 bin = u >> 22; atomicAdd(&hist[lm * 512 + (bin >> 1)], 1u << ((bin & 1) * 16)); }
;     } else if (PASS == 1) {
;       if (valid && (u >> 22) == bA) { const u32 bin = (u >> 12) & 1023u; atomicAdd(&hist[lm * 512 + (bin >> 1)], 1u << ((bin & 1) * 16)); }
; template <int PASS>
; DI void idx_pass(const u16* kp, const bf16x8 (&qf)[8], const float (&wq)[8], int wave, int ntile, int lm, int lg, int tq, bool selall,
;                  u32 bA, u32 pfx, u32* hist, u32* maskw, u32* cand, u32* ccnt) {
;     ...
;   if (kt < ntile - 1) { idx_tile<PASS, false>(ka, qf, wq, kt, lm, lg, tq, selall, bA, pfx, hist, maskw, cand, ccnt); kt += 4; ka = kb; }
.LBB0_622:
	s_or_b64 exec, exec, s[2:3]
	v_lshlrev_b32_e32 v50, 9, v88
	v_cmp_lt_i32_e64 s[4:5], v153, v97
	v_lshlrev_b32_e32 v78, 2, v50
	s_and_saveexec_b64 s[2:3], s[4:5]
	s_cbranch_execz .LBB0_632
	s_waitcnt vmcnt(1)
	v_mfma_f32_16x16x32_bf16 v[50:53], v[42:45], v[38:41], 0
	v_mfma_f32_16x16x32_bf16 v[54:57], v[42:45], v[34:37], 0
	s_nop 6
	v_max_f32_e32 v58, 0, v50
	v_max_f32_e32 v59, 0, v54
	v_pk_mul_f32 v[62:63], v[6:7], v[58:59]
	v_mfma_f32_16x16x32_bf16 v[58:61], v[42:45], v[30:33], 0
	v_add_f32_e32 v50, 0, v62
	v_add_f32_e32 v50, v50, v63
	v_mfma_f32_16x16x32_bf16 v[62:65], v[42:45], v[26:29], 0
	s_nop 4
	v_max_f32_e32 v66, 0, v58
	s_nop 0
	s_nop 0
	v_max_f32_e32 v67, 0, v62
	v_pk_mul_f32 v[70:71], v[8:9], v[66:67]
	v_mfma_f32_16x16x32_bf16 v[66:69], v[42:45], v[22:25], 0
	v_add_f32_e32 v50, v50, v70
	v_add_f32_e32 v50, v50, v71
	v_mfma_f32_16x16x32_bf16 v[70:73], v[42:45], v[18:21], 0
	s_nop 4
	v_max_f32_e32 v74, 0, v66
	s_nop 0
	s_nop 0
	v_max_f32_e32 v75, 0, v70
	v_pk_mul_f32 v[80:81], v[2:3], v[74:75]
	v_mfma_f32_16x16x32_bf16 v[74:77], v[42:45], v[14:17], 0
	v_add_f32_e32 v50, v50, v80
	v_add_f32_e32 v50, v50, v81
	v_mfma_f32_16x16x32_bf16 v[42:45], v[42:45], v[10:13], 0
	s_nop 4
	v_max_f32_e32 v54, v74, v74
	s_nop 1
	v_max_f32_e32 v80, 0, v54
	v_max_f32_e32 v81, 0, v42
	v_pk_mul_f32 v[80:81], v[4:5], v[80:81]
	s_nop 0
	v_add_f32_e32 v42, v50, v80
	v_add_f32_e32 v42, v42, v81
	v_ashrrev_i32_e32 v50, 31, v42
	v_bitop3_b32 v42, v50, v42, s39 bitop3:0x36
	v_lshrrev_b32_e32 v50, 22, v42
	s_waitcnt lgkmcnt(0)
	v_cmp_eq_u32_e64 s[4:5], v50, v137
	s_and_saveexec_b64 s[6:7], s[4:5]
	s_cbranch_execz .LBB0_625
	v_lshrrev_b32_e32 v50, 8, v42
	v_lshrrev_b32_e32 v42, 11, v42
	v_and_b32_e32 v50, 16, v50
	v_and_b32_e32 v42, 0x7fc, v42
	v_lshlrev_b32_e64 v50, v50, 1
	v_add3_u32 v42, v96, v42, v78
	ds_add_u32 v42, v50
.LBB0_625:
	s_or_b64 exec, exec, s[6:7]
	v_max_f32_e32 v42, 0, v51
	v_fma_f32 v42, v6, v42, 0
	v_max_f32_e32 v50, 0, v55
	v_fmac_f32_e32 v42, v7, v50
	v_max_f32_e32 v50, 0, v59
	v_fmac_f32_e32 v42, v8, v50
	v_max_f32_e32 v50, 0, v63
	v_fmac_f32_e32 v42, v9, v50
	v_max_f32_e32 v50, 0, v67
	v_fmac_f32_e32 v42, v2, v50
	v_max_f32_e32 v50, 0, v71
	v_fmac_f32_e32 v42, v3, v50
	v_max_f32_e32 v50, 0, v75
	v_fmac_f32_e32 v42, v4, v50
	v_max_f32_e32 v43, 0, v43
	v_fmac_f32_e32 v42, v5, v43
	v_ashrrev_i32_e32 v43, 31, v42
	v_bitop3_b32 v42, v43, v42, s39 bitop3:0x36
	v_lshrrev_b32_e32 v43, 22, v42
	v_cmp_eq_u32_e64 s[4:5], v43, v137
	s_and_saveexec_b64 s[6:7], s[4:5]
	s_cbranch_execz .LBB0_627
	v_lshrrev_b32_e32 v43, 8, v42
	v_lshrrev_b32_e32 v42, 11, v42
	v_and_b32_e32 v43, 16, v43
	v_and_b32_e32 v42, 0x7fc, v42
	v_lshlrev_b32_e64 v43, v43, 1
	v_add3_u32 v42, v96, v42, v78
	ds_add_u32 v42, v43
.LBB0_627:
	s_or_b64 exec, exec, s[6:7]
	v_max_f32_e32 v42, 0, v52
	v_fma_f32 v42, v6, v42, 0
	v_max_f32_e32 v43, 0, v56
	v_fmac_f32_e32 v42, v7, v43
	v_max_f32_e32 v43, 0, v60
	v_fmac_f32_e32 v42, v8, v43
	v_max_f32_e32 v43, 0, v64
	v_fmac_f32_e32 v42, v9, v43
	v_max_f32_e32 v43, 0, v68
	v_fmac_f32_e32 v42, v2, v43
	v_max_f32_e32 v43, 0, v72
	v_fmac_f32_e32 v42, v3, v43
	v_max_f32_e32 v43, 0, v76
	v_fmac_f32_e32 v42, v4, v43
	v_max_f32_e32 v43, 0, v44
	v_fmac_f32_e32 v42, v5, v43
	v_ashrrev_i32_e32 v43, 31, v42
	v_bitop3_b32 v42, v43, v42, s39 bitop3:0x36
	v_lshrrev_b32_e32 v43, 22, v42
	v_cmp_eq_u32_e64 s[4:5], v43, v137
	s_and_saveexec_b64 s[6:7], s[4:5]
	s_cbranch_execz .LBB0_629
	v_lshrrev_b32_e32 v43, 8, v42
	v_lshrrev_b32_e32 v42, 11, v42
	v_and_b32_e32 v43, 16, v43
	v_and_b32_e32 v42, 0x7fc, v42
	v_lshlrev_b32_e64 v43, v43, 1
	v_add3_u32 v42, v96, v42, v78
	ds_add_u32 v42, v43
.LBB0_629:
	s_or_b64 exec, exec, s[6:7]
	v_max_f32_e32 v42, 0, v53
	v_fma_f32 v42, v6, v42, 0
	v_max_f32_e32 v43, 0, v57
	v_fmac_f32_e32 v42, v7, v43
	v_max_f32_e32 v43, 0, v61
	v_fmac_f32_e32 v42, v8, v43
	v_max_f32_e32 v43, 0, v65
	v_fmac_f32_e32 v42, v9, v43
	v_max_f32_e32 v43, 0, v69
	v_fmac_f32_e32 v42, v2, v43
	v_max_f32_e32 v43, 0, v73
	v_fmac_f32_e32 v42, v3, v43
	v_max_f32_e32 v43, 0, v77
	v_fmac_f32_e32 v42, v4, v43
	v_max_f32_e32 v43, 0, v45
	v_fmac_f32_e32 v42, v5, v43
	v_ashrrev_i32_e32 v43, 31, v42
	v_bitop3_b32 v42, v43, v42, s39 bitop3:0x36
	v_lshrrev_b32_e32 v43, 22, v42
	v_cmp_eq_u32_e64 s[4:5], v43, v137
	s_and_saveexec_b64 s[6:7], s[4:5]
	s_cbranch_execz .LBB0_631
	v_lshrrev_b32_e32 v43, 8, v42
	v_lshrrev_b32_e32 v42, 11, v42
	v_and_b32_e32 v43, 16, v43
	v_and_b32_e32 v42, 0x7fc, v42
	v_lshlrev_b32_e64 v43, v43, 1
	v_add3_u32 v42, v96, v42, v78
	ds_add_u32 v42, v43

; DI f32x4 mfma16(bf16x8 a, bf16x8 b, f32x4 c) { return __builtin_amdgcn_mfma_f32_16x16x32_bf16(a, b, c, 0, 0, 0); }
; template <int PASS, bool DIAG>
; DI void idx_tile(const bf16x8 kf, const bf16x8 (&qf)[8], const float (&wq)[8], int kt, int lm, int lg, int tq, bool selall, u32 bA, u32 pfx,
;                  u32* hist, u32* maskw, u32* cand, u32* ccnt) {
;   const f32x4 z4 = {0.f, 0.f, 0.f, 0.f};
;   f32x4 sc = z4;
; #pragma unroll
;   for (int j = 0; j < 8; ++j) {
;     f32x4 d = mfma16(kf, qf[j], z4);
; #pragma unroll
;     for (int r = 0; r < 4; ++r) sc[r] += wq[j] * fmaxf(d[r], 0.f);
;   }
;   u32 selbits = 0u;
; #pragma unroll
;   for (int r = 0; r < 4; ++r) {
;     const int key = kt * 16 + lg * 4 + r;
;     const bool valid = !DIAG || key <= tq;
;     const u32 bits = __float_as_uint(sc[r]);
;     const u32 u = bits ^ ((u32)((int)bits >> 31) | 0x80000000u);
;     if (PASS == 0) {
;       if (valid) { const u32 bin = u >> 22; atomicAdd(&hist[lm * 512 + (bin >> 1)], 1u << ((bin & 1) * 16)); }
;     } else if (PASS == 1) {
;       if (valid && (u >> 22) == bA) { const u32 bin = (u >> 12) & 1023u; atomicAdd(&hist[lm * 512 + (bin >> 1)], 1u << ((bin & 1) * 16)); }
; template <int PASS>
; DI void idx_pass(const u16* kp, const bf16x8 (&qf)[8], const float (&wq)[8], int wave, int ntile, int lm, int lg, int tq, bool selall,
;                  u32 bA, u32 pfx, u32* hist, u32* maskw, u32* cand, u32* ccnt) {
;     ...
;   if (kt == ntile - 1) idx_tile<PASS, true>(ka, qf, wq, kt, lm, lg, tq, selall, bA, pfx, hist, maskw, cand, ccnt);
.LBB0_632:
	s_or_b64 exec, exec, s[2:3]
	v_cmp_eq_u32_e64 s[4:5], v153, v97
	s_and_saveexec_b64 s[2:3], s[4:5]
	s_cbranch_execz .LBB0_641
	s_waitcnt vmcnt(0)
	v_mfma_f32_16x16x32_bf16 v[46:49], v[42:45], v[38:41], 0
	v_cmp_le_u32_e64 s[4:5], v98, v88
	v_mfma_f32_16x16x32_bf16 v[50:53], v[42:45], v[34:37], 0
	s_nop 5
	v_max_f32_e32 v54, 0, v46
	s_nop 0
	v_max_f32_e32 v55, 0, v50
	v_pk_mul_f32 v[58:59], v[6:7], v[54:55]
	v_mfma_f32_16x16x32_bf16 v[54:57], v[42:45], v[30:33], 0
	v_add_f32_e32 v46, 0, v58
	v_add_f32_e32 v46, v46, v59
	v_mfma_f32_16x16x32_bf16 v[58:61], v[42:45], v[26:29], 0
	s_nop 4
	v_max_f32_e32 v62, 0, v54
	s_nop 0
	s_nop 0
	v_max_f32_e32 v63, 0, v58
	v_pk_mul_f32 v[66:67], v[8:9], v[62:63]
	v_mfma_f32_16x16x32_bf16 v[62:65], v[42:45], v[22:25], 0
	v_add_f32_e32 v46, v46, v66
	v_add_f32_e32 v46, v46, v67
	v_mfma_f32_16x16x32_bf16 v[66:69], v[42:45], v[18:21], 0
	s_nop 4
	v_max_f32_e32 v70, 0, v62
	s_nop 0
	s_nop 0
	v_max_f32_e32 v71, 0, v66
	v_pk_mul_f32 v[74:75], v[2:3], v[70:71]
	v_mfma_f32_16x16x32_bf16 v[70:73], v[42:45], v[14:17], 0
	v_add_f32_e32 v46, v46, v74
	v_add_f32_e32 v46, v46, v75
	v_mfma_f32_16x16x32_bf16 v[42:45], v[42:45], v[10:13], 0
	s_nop 4
	v_max_f32_e32 v50, v70, v70
	s_nop 1
	v_max_f32_e32 v74, 0, v50
	v_max_f32_e32 v75, 0, v42
	v_pk_mul_f32 v[74:75], v[4:5], v[74:75]
	s_nop 0
	v_add_f32_e32 v42, v46, v74
	v_add_f32_e32 v42, v42, v75
	v_ashrrev_i32_e32 v46, 31, v42
	v_bitop3_b32 v42, v46, v42, s39 bitop3:0x36
	v_lshrrev_b32_e32 v46, 22, v42
	s_waitcnt lgkmcnt(0)
	v_cmp_eq_u32_e64 s[6:7], v46, v137
	s_and_b64 s[6:7], s[4:5], s[6:7]
	s_and_saveexec_b64 s[4:5], s[6:7]
	s_cbranch_execz .LBB0_635
	v_lshrrev_b32_e32 v46, 8, v42
	v_lshrrev_b32_e32 v42, 11, v42
	v_and_b32_e32 v46, 16, v46
	v_and_b32_e32 v42, 0x7fc, v42
	v_lshlrev_b32_e64 v46, v46, 1
	v_add3_u32 v42, v96, v42, v78
	ds_add_u32 v42, v46
.LBB0_635:
	s_or_b64 exec, exec, s[4:5]
	v_max_f32_e32 v42, 0, v47
	v_fma_f32 v42, v6, v42, 0
	v_max_f32_e32 v46, 0, v51
	v_fmac_f32_e32 v42, v7, v46
	v_max_f32_e32 v46, 0, v55
	v_fmac_f32_e32 v42, v8, v46
	v_max_f32_e32 v46, 0, v59
	v_fmac_f32_e32 v42, v9, v46
	v_max_f32_e32 v46, 0, v63
	v_fmac_f32_e32 v42, v2, v46
	v_max_f32_e32 v46, 0, v67
	v_fmac_f32_e32 v42, v3, v46
	v_max_f32_e32 v46, 0, v71
	v_fmac_f32_e32 v42, v4, v46
	v_max_f32_e32 v43, 0, v43
	v_fmac_f32_e32 v42, v5, v43
	v_ashrrev_i32_e32 v43, 31, v42
	v_bitop3_b32 v42, v43, v42, s39 bitop3:0x36
	v_lshrrev_b32_e32 v43, 22, v42
	v_cmp_lt_u32_e64 s[4:5], v98, v88
	v_cmp_eq_u32_e64 s[6:7], v43, v137
	s_and_b64 s[6:7], s[4:5], s[6:7]
	s_and_saveexec_b64 s[4:5], s[6:7]
	s_cbranch_execz .LBB0_637
	v_lshrrev_b32_e32 v43, 8, v42
	v_lshrrev_b32_e32 v42, 11, v42
	v_and_b32_e32 v43, 16, v43
	v_and_b32_e32 v42, 0x7fc, v42
	v_lshlrev_b32_e64 v43, v43, 1
	v_add3_u32 v42, v96, v42, v78
	ds_add_u32 v42, v43
.LBB0_637:
	s_or_b64 exec, exec, s[4:5]
	v_max_f32_e32 v42, 0, v48
	v_fma_f32 v43, v6, v42, 0
	v_max_f32_e32 v42, 0, v52
	v_fmac_f32_e32 v43, v7, v42
	v_max_f32_e32 v42, 0, v56
	v_fmac_f32_e32 v43, v8, v42
	v_max_f32_e32 v42, 0, v60
	v_fmac_f32_e32 v43, v9, v42
	v_max_f32_e32 v42, 0, v64
	v_fmac_f32_e32 v43, v2, v42
	v_max_f32_e32 v42, 0, v68
	v_fmac_f32_e32 v43, v3, v42
	v_max_f32_e32 v42, 0, v72
	v_fmac_f32_e32 v43, v4, v42
	v_max_f32_e32 v42, 0, v44
	v_fmac_f32_e32 v43, v5, v42
	v_or_b32_e32 v42, v98, v87
	v_or_b32_e32 v44, 2, v42
	v_cmp_le_u32_e64 s[4:5], v44, v108
	v_ashrrev_i32_e32 v44, 31, v43
	v_bitop3_b32 v43, v44, v43, s39 bitop3:0x36
	v_lshrrev_b32_e32 v44, 22, v43
	v_cmp_eq_u32_e64 s[6:7], v44, v137
	s_and_b64 s[6:7], s[4:5], s[6:7]
	s_and_saveexec_b64 s[4:5], s[6:7]
	s_cbranch_execz .LBB0_639
	v_lshrrev_b32_e32 v44, 8, v43
	v_lshrrev_b32_e32 v43, 11, v43
	v_and_b32_e32 v44, 16, v44
	v_and_b32_e32 v43, 0x7fc, v43
	v_lshlrev_b32_e64 v44, v44, 1
	v_add3_u32 v43, v96, v43, v78
	ds_add_u32 v43, v44
.LBB0_639:
	s_or_b64 exec, exec, s[4:5]
	v_max_f32_e32 v43, 0, v49
	v_fma_f32 v43, v6, v43, 0
	v_max_f32_e32 v44, 0, v53
	v_fmac_f32_e32 v43, v7, v44
	v_max_f32_e32 v44, 0, v57
	v_fmac_f32_e32 v43, v8, v44
	v_max_f32_e32 v44, 0, v61
	v_fmac_f32_e32 v43, v9, v44
	v_max_f32_e32 v44, 0, v65
	v_fmac_f32_e32 v43, v2, v44
	v_max_f32_e32 v44, 0, v69
	v_fmac_f32_e32 v43, v3, v44
	v_max_f32_e32 v44, 0, v73
	v_fmac_f32_e32 v43, v4, v44
	v_max_f32_e32 v44, 0, v45
	v_fmac_f32_e32 v43, v5, v44
	v_or_b32_e32 v42, 3, v42
	v_cmp_le_u32_e64 s[4:5], v42, v108
	v_ashrrev_i32_e32 v42, 31, v43
	v_bitop3_b32 v42, v42, v43, s39 bitop3:0x36
	v_lshrrev_b32_e32 v43, 22, v42
	v_cmp_eq_u32_e64 s[6:7], v43, v137
	s_and_b64 s[4:5], s[4:5], s[6:7]
	s_and_b64 exec, exec, s[4:5]
	s_cbranch_execz .LBB0_641
	v_lshrrev_b32_e32 v43, 8, v42
	v_lshrrev_b32_e32 v42, 11, v42
	v_and_b32_e32 v43, 16, v43
	v_and_b32_e32 v42, 0x7fc, v42
	v_lshlrev_b32_e64 v43, v43, 1
	v_add3_u32 v42, v96, v42, v78
	ds_add_u32 v42, v43

; DI f32x4 mfma16(bf16x8 a, bf16x8 b, f32x4 c) { return __builtin_amdgcn_mfma_f32_16x16x32_bf16(a, b, c, 0, 0, 0); }
; template <int PASS, bool DIAG>
; DI void idx_tile(const bf16x8 kf, const bf16x8 (&qf)[8], const float (&wq)[8], int kt, int lm, int lg, int tq, bool selall, u32 bA, u32 pfx,
;                  u32* hist, u32* maskw, u32* cand, u32* ccnt) {
;   const f32x4 z4 = {0.f, 0.f, 0.f, 0.f};
;   f32x4 sc = z4;
; #pragma unroll
;   for (int j = 0; j < 8; ++j) {
;     f32x4 d = mfma16(kf, qf[j], z4);
; #pragma unroll
;     for (int r = 0; r < 4; ++r) sc[r] += wq[j] * fmaxf(d[r], 0.f);
;   }
;   u32 selbits = 0u;
; #pragma unroll
;   for (int r = 0; r < 4; ++r) {
;     const int key = kt * 16 + lg * 4 + r;
;     const bool valid = !DIAG || key <= tq;
;     const u32 bits = __float_as_uint(sc[r]);
;     const u32 u = bits ^ ((u32)((int)bits >> 31) | 0x80000000u);
;     if (PASS == 0) {
;       if (valid) { const u32 bin = u >> 22; atomicAdd(&hist[lm * 512 + (bin >> 1)], 1u << ((bin & 1) * 16)); }
;     } else if (PASS == 1) {
;       if (valid && (u >> 22) == bA) { const u32 bin = (u >> 12) & 1023u; atomicAdd(&hist[lm * 512 + (bin >> 1)], 1u << ((bin & 1) * 16)); }
;     } else {
;       const u32 pp = u >> 12;
;       if (valid && (selall || pp > pfx)) selbits |= 1u << r;
;       if (valid && !selall && pp == pfx) {
;         const u32 ix = atomicAdd(&ccnt[lm], 1u);
;         if (ix < 64u) { cand[(lm * 64 + ix) * 2] = u; cand[(lm * 64 + ix) * 2 + 1] = (u32)key; }
;       }
;     }
;   }
; template <int PASS>
; DI void idx_pass(const u16* kp, const bf16x8 (&qf)[8], const float (&wq)[8], int wave, int ntile, int lm, int lg, int tq, bool selall,
;                  u32 bA, u32 pfx, u32* hist, u32* maskw, u32* cand, u32* ccnt) {
;     ...
;   for (; kt + 4 < ntile - 1; kt += 8) {
;     const bf16x8 kc = ldk(kt + 8), kd = ldk(kt + 12);
;     idx_tile<PASS, false>(ka, qf, wq, kt, lm, lg, tq, selall, bA, pfx, hist, maskw, cand, ccnt);
;     idx_tile<PASS, false>(kb, qf, wq, kt + 4, lm, lg, tq, selall, bA, pfx, hist, maskw, cand, ccnt);
;     ka = kc; kb = kd;
.LBB0_834:
	v_add_u32_e32 v103, 8, v109
	s_waitcnt vmcnt(1)
	v_mov_b64_e32 v[84:85], v[44:45]
	v_cmp_le_i32_e32 vcc, v103, v97
	v_add_u32_e32 v0, 12, v109
	v_mov_b64_e32 v[82:83], v[42:43]
	v_cndmask_b32_e32 v42, 0, v103, vcc
	v_cmp_le_i32_e32 vcc, v0, v97
	v_ashrrev_i32_e32 v43, 31, v42
	v_lshlrev_b64 v[42:43], 10, v[42:43]
	v_cndmask_b32_e32 v44, 0, v0, vcc
	v_ashrrev_i32_e32 v45, 31, v44
	v_lshlrev_b64 v[44:45], 10, v[44:45]
	v_lshl_add_u64 v[42:43], v[90:91], 0, v[42:43]
	v_lshl_add_u64 v[50:51], v[90:91], 0, v[44:45]
	global_load_dwordx4 v[42:45], v[42:43], off
	s_nop 0
	global_load_dwordx4 v[50:53], v[50:51], off
	v_mfma_f32_16x16x32_bf16 v[54:57], v[82:85], v[38:41], 0
	v_mfma_f32_16x16x32_bf16 v[58:61], v[82:85], v[34:37], 0
	s_nop 6
	v_max_f32_e32 v62, 0, v54
	v_max_f32_e32 v63, 0, v58
	v_pk_mul_f32 v[66:67], v[6:7], v[62:63]
	v_mfma_f32_16x16x32_bf16 v[62:65], v[82:85], v[30:33], 0
	v_add_f32_e32 v0, 0, v66
	v_add_f32_e32 v0, v0, v67
	v_mfma_f32_16x16x32_bf16 v[66:69], v[82:85], v[26:29], 0
	s_nop 4
	v_max_f32_e32 v70, 0, v62
	s_nop 0
	s_nop 0
	v_max_f32_e32 v71, 0, v66
	v_pk_mul_f32 v[74:75], v[8:9], v[70:71]
	v_mfma_f32_16x16x32_bf16 v[70:73], v[82:85], v[22:25], 0
	v_add_f32_e32 v0, v0, v74
	v_add_f32_e32 v0, v0, v75
	v_mfma_f32_16x16x32_bf16 v[74:77], v[82:85], v[18:21], 0
	s_nop 4
	v_max_f32_e32 v78, 0, v70
	s_nop 0
	s_nop 0
	v_max_f32_e32 v79, 0, v74
	v_pk_mul_f32 v[92:93], v[2:3], v[78:79]
	v_mfma_f32_16x16x32_bf16 v[78:81], v[82:85], v[14:17], 0
	v_add_f32_e32 v0, v0, v92
	v_add_f32_e32 v0, v0, v93
	v_mfma_f32_16x16x32_bf16 v[82:85], v[82:85], v[10:13], 0
	s_nop 4
	v_max_f32_e32 v92, 0, v78
	s_nop 0
	s_nop 0
	v_max_f32_e32 v93, 0, v82
	v_pk_mul_f32 v[92:93], v[4:5], v[92:93]
	s_nop 0
	v_add_f32_e32 v0, v0, v92
	v_add_f32_e32 v0, v0, v93
	v_ashrrev_i32_e32 v54, 31, v0
	v_bitop3_b32 v94, v54, v0, s39 bitop3:0x36
	v_lshrrev_b32_e32 v0, 12, v94
	v_cmp_eq_u32_e32 vcc, v0, v99
	v_add_u32_e32 v93, v98, v102
	s_and_b64 s[28:29], s[6:7], vcc
	s_and_saveexec_b64 s[8:9], s[28:29]
	s_cbranch_execz .LBB0_837
	ds_add_rtn_u32 v54, v136, v203 offset:49408
	s_waitcnt lgkmcnt(0)
	v_cmp_gt_u32_e32 vcc, 64, v54
	s_and_b64 exec, exec, vcc
	v_subrev_u32_e32 v95, 64, v93
	v_lshl_add_u32 v54, v54, 3, v100
	ds_write_b64 v54, v[94:95] offset:41216
.LBB0_837:
	s_or_b64 exec, exec, s[8:9]
	v_max_f32_e32 v54, 0, v55
	v_fma_f32 v54, v6, v54, 0
	v_max_f32_e32 v55, 0, v59
	v_fmac_f32_e32 v54, v7, v55
	v_max_f32_e32 v55, 0, v63
	v_fmac_f32_e32 v54, v8, v55
	v_max_f32_e32 v55, 0, v67
	v_fmac_f32_e32 v54, v9, v55
	v_max_f32_e32 v55, 0, v71
	v_fmac_f32_e32 v54, v2, v55
	v_max_f32_e32 v55, 0, v75
	v_fmac_f32_e32 v54, v3, v55
	v_max_f32_e32 v55, 0, v79
	v_fmac_f32_e32 v54, v4, v55
	v_max_f32_e32 v55, 0, v83
	v_fmac_f32_e32 v54, v5, v55
	v_ashrrev_i32_e32 v55, 31, v54
	v_bitop3_b32 v54, v55, v54, s39 bitop3:0x36
	v_lshrrev_b32_e32 v58, 12, v54
	v_cmp_eq_u32_e32 vcc, v58, v99
	s_and_b64 s[28:29], s[6:7], vcc
	s_and_saveexec_b64 s[8:9], s[28:29]
	s_cbranch_execz .LBB0_840
	ds_add_rtn_u32 v59, v136, v203 offset:49408
	s_waitcnt lgkmcnt(0)
	v_cmp_gt_u32_e32 vcc, 64, v59
	s_and_b64 exec, exec, vcc
	v_subrev_u32_e32 v55, 63, v93
	v_lshl_add_u32 v59, v59, 3, v100
	ds_write_b64 v59, v[54:55] offset:41216
.LBB0_840:
	s_or_b64 exec, exec, s[8:9]
	v_max_f32_e32 v54, 0, v56
	v_fma_f32 v54, v6, v54, 0
	v_max_f32_e32 v55, 0, v60
	v_fmac_f32_e32 v54, v7, v55
	v_max_f32_e32 v55, 0, v64
	v_fmac_f32_e32 v54, v8, v55
	v_max_f32_e32 v55, 0, v68
	v_fmac_f32_e32 v54, v9, v55
	v_max_f32_e32 v55, 0, v72
	v_fmac_f32_e32 v54, v2, v55
	v_max_f32_e32 v55, 0, v76
	v_fmac_f32_e32 v54, v3, v55
	v_max_f32_e32 v55, 0, v80
	v_fmac_f32_e32 v54, v4, v55
	v_max_f32_e32 v55, 0, v84
	v_fmac_f32_e32 v54, v5, v55
	v_ashrrev_i32_e32 v55, 31, v54
	v_bitop3_b32 v54, v55, v54, s39 bitop3:0x36
	v_lshrrev_b32_e32 v56, 12, v54
	v_cmp_eq_u32_e32 vcc, v56, v99
	s_and_b64 s[28:29], s[6:7], vcc
	s_and_saveexec_b64 s[8:9], s[28:29]
	s_cbranch_execz .LBB0_843
	ds_add_rtn_u32 v59, v136, v203 offset:49408
	s_waitcnt lgkmcnt(0)
	v_cmp_gt_u32_e32 vcc, 64, v59
	s_and_b64 exec, exec, vcc
	v_subrev_u32_e32 v55, 62, v93
	v_lshl_add_u32 v59, v59, 3, v100
	ds_write_b64 v59, v[54:55] offset:41216
.LBB0_843:
	s_or_b64 exec, exec, s[8:9]
	v_max_f32_e32 v54, 0, v57
	v_fma_f32 v54, v6, v54, 0
	v_max_f32_e32 v55, 0, v61
	v_fmac_f32_e32 v54, v7, v55
	v_max_f32_e32 v55, 0, v65
	v_fmac_f32_e32 v54, v8, v55
	v_max_f32_e32 v55, 0, v69
	v_fmac_f32_e32 v54, v9, v55
	v_max_f32_e32 v55, 0, v73
	v_fmac_f32_e32 v54, v2, v55
	v_max_f32_e32 v55, 0, v77
	v_fmac_f32_e32 v54, v3, v55
	v_max_f32_e32 v55, 0, v81
	v_fmac_f32_e32 v54, v4, v55
	v_max_f32_e32 v55, 0, v85
	v_fmac_f32_e32 v54, v5, v55
	v_ashrrev_i32_e32 v55, 31, v54
	v_bitop3_b32 v54, v55, v54, s39 bitop3:0x36
	v_lshrrev_b32_e32 v57, 12, v54
	v_cmp_eq_u32_e32 vcc, v57, v99
	s_and_b64 s[28:29], s[6:7], vcc
	s_and_saveexec_b64 s[8:9], s[28:29]
	s_cbranch_execz .LBB0_846
	ds_add_rtn_u32 v59, v136, v203 offset:49408
	s_waitcnt lgkmcnt(0)
	v_cmp_gt_u32_e32 vcc, 64, v59
	s_and_b64 exec, exec, vcc
	v_subrev_u32_e32 v55, 61, v93
	v_lshl_add_u32 v59, v59, 3, v100
	ds_write_b64 v59, v[54:55] offset:41216

; DI f32x4 mfma16(bf16x8 a, bf16x8 b, f32x4 c) { return __builtin_amdgcn_mfma_f32_16x16x32_bf16(a, b, c, 0, 0, 0); }
; template <int PASS, bool DIAG>
; DI void idx_tile(const bf16x8 kf, const bf16x8 (&qf)[8], const float (&wq)[8], int kt, int lm, int lg, int tq, bool selall, u32 bA, u32 pfx,
;                  u32* hist, u32* maskw, u32* cand, u32* ccnt) {
;   const f32x4 z4 = {0.f, 0.f, 0.f, 0.f};
;   f32x4 sc = z4;
; #pragma unroll
;   for (int j = 0; j < 8; ++j) {
;     f32x4 d = mfma16(kf, qf[j], z4);
; #pragma unroll
;     for (int r = 0; r < 4; ++r) sc[r] += wq[j] * fmaxf(d[r], 0.f);
;   }
;   u32 selbits = 0u;
; #pragma unroll
;   for (int r = 0; r < 4; ++r) {
;     const int key = kt * 16 + lg * 4 + r;
;     const bool valid = !DIAG || key <= tq;
;     const u32 bits = __float_as_uint(sc[r]);
;     const u32 u = bits ^ ((u32)((int)bits >> 31) | 0x80000000u);
;     if (PASS == 0) {
;       if (valid) { const u32 bin = u >> 22; atomicAdd(&hist[lm * 512 + (bin >> 1)], 1u << ((bin & 1) * 16)); }
;     } else if (PASS == 1) {
;       if (valid && (u >> 22) == bA) { const u32 bin = (u >> 12) & 1023u; atomicAdd(&hist[lm * 512 + (bin >> 1)], 1u << ((bin & 1) * 16)); }
;     } else {
;       const u32 pp = u >> 12;
;       if (valid && (selall || pp > pfx)) selbits |= 1u << r;
;       if (valid && !selall && pp == pfx) {
;         const u32 ix = atomicAdd(&ccnt[lm], 1u);
;         if (ix < 64u) { cand[(lm * 64 + ix) * 2] = u; cand[(lm * 64 + ix) * 2 + 1] = (u32)key; }
;       }
;     }
;   }
; template <int PASS>
; DI void idx_pass(const u16* kp, const bf16x8 (&qf)[8], const float (&wq)[8], int wave, int ntile, int lm, int lg, int tq, bool selall,
;                  u32 bA, u32 pfx, u32* hist, u32* maskw, u32* cand, u32* ccnt) {
;     ...
;   for (; kt + 4 < ntile - 1; kt += 8) {
;     const bf16x8 kc = ldk(kt + 8), kd = ldk(kt + 12);
;     idx_tile<PASS, false>(ka, qf, wq, kt, lm, lg, tq, selall, bA, pfx, hist, maskw, cand, ccnt);
;     idx_tile<PASS, false>(kb, qf, wq, kt + 4, lm, lg, tq, selall, bA, pfx, hist, maskw, cand, ccnt);
;     ka = kc; kb = kd;
.LBB0_848:
	s_or_b64 exec, exec, s[8:9]
	s_waitcnt vmcnt(2)
	v_mfma_f32_16x16x32_bf16 v[54:57], v[46:49], v[38:41], 0
	v_mfma_f32_16x16x32_bf16 v[58:61], v[46:49], v[34:37], 0
	s_nop 6
	v_max_f32_e32 v62, 0, v54
	v_max_f32_e32 v63, 0, v58
	v_pk_mul_f32 v[66:67], v[6:7], v[62:63]
	v_mfma_f32_16x16x32_bf16 v[62:65], v[46:49], v[30:33], 0
	v_add_f32_e32 v0, 0, v66
	v_add_f32_e32 v0, v0, v67
	v_mfma_f32_16x16x32_bf16 v[66:69], v[46:49], v[26:29], 0
	s_nop 4
	v_max_f32_e32 v70, 0, v62
	s_nop 0
	s_nop 0
	v_max_f32_e32 v71, 0, v66
	v_pk_mul_f32 v[74:75], v[8:9], v[70:71]
	v_mfma_f32_16x16x32_bf16 v[70:73], v[46:49], v[22:25], 0
	v_add_f32_e32 v0, v0, v74
	v_add_f32_e32 v0, v0, v75
	v_mfma_f32_16x16x32_bf16 v[74:77], v[46:49], v[18:21], 0
	s_nop 4
	v_max_f32_e32 v78, 0, v70
	s_nop 0
	s_nop 0
	v_max_f32_e32 v79, 0, v74
	v_pk_mul_f32 v[82:83], v[2:3], v[78:79]
	v_mfma_f32_16x16x32_bf16 v[78:81], v[46:49], v[14:17], 0
	v_add_f32_e32 v0, v0, v82
	v_add_f32_e32 v0, v0, v83
	v_mfma_f32_16x16x32_bf16 v[46:49], v[46:49], v[10:13], 0
	s_nop 4
	v_max_f32_e32 v54, v78, v78
	s_nop 1
	v_max_f32_e32 v82, 0, v54
	v_max_f32_e32 v83, 0, v46
	v_pk_mul_f32 v[82:83], v[4:5], v[82:83]
	s_nop 0
	v_add_f32_e32 v0, v0, v82
	v_add_f32_e32 v0, v0, v83
	v_ashrrev_i32_e32 v46, 31, v0
	v_bitop3_b32 v92, v46, v0, s39 bitop3:0x36
	v_lshrrev_b32_e32 v0, 12, v92
	v_cmp_eq_u32_e32 vcc, v0, v99
	s_and_b64 s[28:29], s[6:7], vcc
	s_and_saveexec_b64 s[8:9], s[28:29]
	s_cbranch_execz .LBB0_851
	ds_add_rtn_u32 v46, v136, v203 offset:49408
	s_waitcnt lgkmcnt(0)
	v_cmp_gt_u32_e32 vcc, 64, v46
	s_and_b64 exec, exec, vcc
	v_lshl_add_u32 v46, v46, 3, v100
	ds_write_b64 v46, v[92:93] offset:41216
.LBB0_851:
	s_or_b64 exec, exec, s[8:9]
	v_max_f32_e32 v46, 0, v55
	v_fma_f32 v46, v6, v46, 0
	v_max_f32_e32 v54, 0, v59
	v_fmac_f32_e32 v46, v7, v54
	v_max_f32_e32 v54, 0, v63
	v_fmac_f32_e32 v46, v8, v54
	v_max_f32_e32 v54, 0, v67
	v_fmac_f32_e32 v46, v9, v54
	v_max_f32_e32 v54, 0, v71
	v_fmac_f32_e32 v46, v2, v54
	v_max_f32_e32 v54, 0, v75
	v_fmac_f32_e32 v46, v3, v54
	v_max_f32_e32 v54, 0, v79
	v_fmac_f32_e32 v46, v4, v54
	v_max_f32_e32 v47, 0, v47
	v_fmac_f32_e32 v46, v5, v47
	v_ashrrev_i32_e32 v47, 31, v46
	v_bitop3_b32 v46, v47, v46, s39 bitop3:0x36
	v_lshrrev_b32_e32 v54, 12, v46
	v_cmp_eq_u32_e32 vcc, v54, v99
	s_and_b64 s[28:29], s[6:7], vcc
	s_and_saveexec_b64 s[8:9], s[28:29]
	s_cbranch_execz .LBB0_854
	ds_add_rtn_u32 v55, v136, v203 offset:49408
	s_waitcnt lgkmcnt(0)
	v_cmp_gt_u32_e32 vcc, 64, v55
	s_and_b64 exec, exec, vcc
	v_add_u32_e32 v47, 1, v93
	v_lshl_add_u32 v55, v55, 3, v100
	ds_write_b64 v55, v[46:47] offset:41216
.LBB0_854:
	s_or_b64 exec, exec, s[8:9]
	v_max_f32_e32 v46, 0, v56
	v_fma_f32 v46, v6, v46, 0
	v_max_f32_e32 v47, 0, v60
	v_fmac_f32_e32 v46, v7, v47
	v_max_f32_e32 v47, 0, v64
	v_fmac_f32_e32 v46, v8, v47
	v_max_f32_e32 v47, 0, v68
	v_fmac_f32_e32 v46, v9, v47
	v_max_f32_e32 v47, 0, v72
	v_fmac_f32_e32 v46, v2, v47
	v_max_f32_e32 v47, 0, v76
	v_fmac_f32_e32 v46, v3, v47
	v_max_f32_e32 v47, 0, v80
	v_fmac_f32_e32 v46, v4, v47
	v_max_f32_e32 v47, 0, v48
	v_fmac_f32_e32 v46, v5, v47
	v_ashrrev_i32_e32 v47, 31, v46
	v_bitop3_b32 v46, v47, v46, s39 bitop3:0x36
	v_lshrrev_b32_e32 v48, 12, v46
	v_cmp_eq_u32_e32 vcc, v48, v99
	s_and_b64 s[28:29], s[6:7], vcc
	s_and_saveexec_b64 s[8:9], s[28:29]
	s_cbranch_execz .LBB0_857
	ds_add_rtn_u32 v55, v136, v203 offset:49408
	s_waitcnt lgkmcnt(0)
	v_cmp_gt_u32_e32 vcc, 64, v55
	s_and_b64 exec, exec, vcc
	v_add_u32_e32 v47, 2, v93
	v_lshl_add_u32 v55, v55, 3, v100
	ds_write_b64 v55, v[46:47] offset:41216
.LBB0_857:
	s_or_b64 exec, exec, s[8:9]
	v_max_f32_e32 v46, 0, v57
	v_fma_f32 v46, v6, v46, 0
	v_max_f32_e32 v47, 0, v61
	v_fmac_f32_e32 v46, v7, v47
	v_max_f32_e32 v47, 0, v65
	v_fmac_f32_e32 v46, v8, v47
	v_max_f32_e32 v47, 0, v69
	v_fmac_f32_e32 v46, v9, v47
	v_max_f32_e32 v47, 0, v73
	v_fmac_f32_e32 v46, v2, v47
	v_max_f32_e32 v47, 0, v77
	v_fmac_f32_e32 v46, v3, v47
	v_max_f32_e32 v47, 0, v81
	v_fmac_f32_e32 v46, v4, v47
	v_max_f32_e32 v47, 0, v49
	v_fmac_f32_e32 v46, v5, v47
	v_ashrrev_i32_e32 v47, 31, v46
	v_bitop3_b32 v46, v47, v46, s39 bitop3:0x36
	v_lshrrev_b32_e32 v49, 12, v46
	v_cmp_eq_u32_e32 vcc, v49, v99
	s_and_b64 s[28:29], s[6:7], vcc
	s_and_saveexec_b64 s[8:9], s[28:29]
	s_cbranch_execz .LBB0_860
	ds_add_rtn_u32 v55, v136, v203 offset:49408
	s_waitcnt lgkmcnt(0)
	v_cmp_gt_u32_e32 vcc, 64, v55
	s_and_b64 exec, exec, vcc
	v_add_u32_e32 v47, 3, v93
	v_lshl_add_u32 v55, v55, 3, v100
	ds_write_b64 v55, v[46:47] offset:41216

; DI f32x4 mfma16(bf16x8 a, bf16x8 b, f32x4 c) { return __builtin_amdgcn_mfma_f32_16x16x32_bf16(a, b, c, 0, 0, 0); }
; template <int PASS, bool DIAG>
; DI void idx_tile(const bf16x8 kf, const bf16x8 (&qf)[8], const float (&wq)[8], int kt, int lm, int lg, int tq, bool selall, u32 bA, u32 pfx,
;                  u32* hist, u32* maskw, u32* cand, u32* ccnt) {
;   const f32x4 z4 = {0.f, 0.f, 0.f, 0.f};
;   f32x4 sc = z4;
; #pragma unroll
;   for (int j = 0; j < 8; ++j) {
;     f32x4 d = mfma16(kf, qf[j], z4);
; #pragma unroll
;     for (int r = 0; r < 4; ++r) sc[r] += wq[j] * fmaxf(d[r], 0.f);
;   }
;   u32 selbits = 0u;
; #pragma unroll
;   for (int r = 0; r < 4; ++r) {
;     const int key = kt * 16 + lg * 4 + r;
;     const bool valid = !DIAG || key <= tq;
;     const u32 bits = __float_as_uint(sc[r]);
;     const u32 u = bits ^ ((u32)((int)bits >> 31) | 0x80000000u);
;     if (PASS == 0) {
;       if (valid) { const u32 bin = u >> 22; atomicAdd(&hist[lm * 512 + (bin >> 1)], 1u << ((bin & 1) * 16)); }
;     } else if (PASS == 1) {
;       if (valid && (u >> 22) == bA) { const u32 bin = (u >> 12) & 1023u; atomicAdd(&hist[lm * 512 + (bin >> 1)], 1u << ((bin & 1) * 16)); }
;     } else {
;       const u32 pp = u >> 12;
;       if (valid && (selall || pp > pfx)) selbits |= 1u << r;
;       if (valid && !selall && pp == pfx) {
;         const u32 ix = atomicAdd(&ccnt[lm], 1u);
;         if (ix < 64u) { cand[(lm * 64 + ix) * 2] = u; cand[(lm * 64 + ix) * 2 + 1] = (u32)key; }
;       }
;     }
;   }
; template <int PASS>
; DI void idx_pass(const u16* kp, const bf16x8 (&qf)[8], const float (&wq)[8], int wave, int ntile, int lm, int lg, int tq, bool selall,
;                  u32 bA, u32 pfx, u32* hist, u32* maskw, u32* cand, u32* ccnt) {
;     ...
;   if (kt < ntile - 1) { idx_tile<PASS, false>(ka, qf, wq, kt, lm, lg, tq, selall, bA, pfx, hist, maskw, cand, ccnt); kt += 4; ka = kb; }
.LBB0_863:
	s_or_b64 exec, exec, s[2:3]
	v_cmp_lt_i32_e32 vcc, v109, v97
	v_lshlrev_b32_e32 v80, 7, v88
	s_and_saveexec_b64 s[2:3], vcc
	s_cbranch_execz .LBB0_879
	s_waitcnt vmcnt(1)
	v_mfma_f32_16x16x32_bf16 v[50:53], v[42:45], v[38:41], 0
	s_xor_b64 s[4:5], s[40:41], -1
	v_mfma_f32_16x16x32_bf16 v[54:57], v[42:45], v[34:37], 0
	s_nop 5
	v_max_f32_e32 v58, 0, v50
	s_nop 0
	v_max_f32_e32 v59, 0, v54
	v_pk_mul_f32 v[62:63], v[6:7], v[58:59]
	v_mfma_f32_16x16x32_bf16 v[58:61], v[42:45], v[30:33], 0
	v_add_f32_e32 v50, 0, v62
	v_add_f32_e32 v50, v50, v63
	v_mfma_f32_16x16x32_bf16 v[62:65], v[42:45], v[26:29], 0
	s_nop 4
	v_max_f32_e32 v66, 0, v58
	s_nop 0
	s_nop 0
	v_max_f32_e32 v67, 0, v62
	v_pk_mul_f32 v[70:71], v[8:9], v[66:67]
	v_mfma_f32_16x16x32_bf16 v[66:69], v[42:45], v[22:25], 0
	v_add_f32_e32 v50, v50, v70
	v_add_f32_e32 v50, v50, v71
	v_mfma_f32_16x16x32_bf16 v[70:73], v[42:45], v[18:21], 0
	s_nop 4
	v_max_f32_e32 v74, 0, v66
	s_nop 0
	s_nop 0
	v_max_f32_e32 v75, 0, v70
	v_pk_mul_f32 v[78:79], v[2:3], v[74:75]
	v_mfma_f32_16x16x32_bf16 v[74:77], v[42:45], v[14:17], 0
	v_add_f32_e32 v50, v50, v78
	v_add_f32_e32 v50, v50, v79
	v_mfma_f32_16x16x32_bf16 v[42:45], v[42:45], v[10:13], 0
	s_nop 4
	s_nop 1
	v_max_f32_e32 v78, 0, v74
	v_max_f32_e32 v79, 0, v42
	v_pk_mul_f32 v[78:79], v[4:5], v[78:79]
	s_nop 0
	v_add_f32_e32 v42, v50, v78
	v_add_f32_e32 v42, v42, v79
	v_ashrrev_i32_e32 v54, 31, v42
	v_bitop3_b32 v78, v54, v42, s39 bitop3:0x36
	v_lshrrev_b32_e32 v54, 12, v78
	v_lshlrev_b32_e32 v50, 4, v109
	v_cmp_eq_u32_e32 vcc, v54, v99
	v_or_b32_e32 v79, v50, v98
	s_and_b64 s[8:9], s[4:5], vcc
	s_and_saveexec_b64 s[6:7], s[8:9]
	s_cbranch_execz .LBB0_867
	ds_add_rtn_u32 v42, v136, v203 offset:49408
	s_waitcnt lgkmcnt(0)
	v_cmp_gt_u32_e32 vcc, 64, v42
	s_and_b64 exec, exec, vcc
	v_lshlrev_b32_e32 v42, 3, v42
	v_lshlrev_b32_e32 v58, 2, v80
	v_add3_u32 v42, v96, v42, v58
	ds_write_b64 v42, v[78:79] offset:41216
.LBB0_867:
	s_or_b64 exec, exec, s[6:7]
	v_max_f32_e32 v42, 0, v51
	v_fma_f32 v42, v6, v42, 0
	v_max_f32_e32 v51, 0, v55
	v_fmac_f32_e32 v42, v7, v51
	v_max_f32_e32 v51, 0, v59
	v_fmac_f32_e32 v42, v8, v51
	v_max_f32_e32 v51, 0, v63
	v_fmac_f32_e32 v42, v9, v51
	v_max_f32_e32 v51, 0, v67
	v_fmac_f32_e32 v42, v2, v51
	v_max_f32_e32 v51, 0, v71
	v_fmac_f32_e32 v42, v3, v51
	v_max_f32_e32 v51, 0, v75
	v_fmac_f32_e32 v42, v4, v51
	v_max_f32_e32 v43, 0, v43
	v_fmac_f32_e32 v42, v5, v43
	v_ashrrev_i32_e32 v43, 31, v42
	v_bitop3_b32 v42, v43, v42, s39 bitop3:0x36
	v_lshrrev_b32_e32 v51, 12, v42
	v_cmp_eq_u32_e32 vcc, v51, v99
	s_and_b64 s[8:9], s[4:5], vcc
	s_and_saveexec_b64 s[6:7], s[8:9]
	s_cbranch_execz .LBB0_870
	ds_add_rtn_u32 v55, v136, v203 offset:49408
	s_waitcnt lgkmcnt(0)
	v_cmp_gt_u32_e32 vcc, 64, v55
	s_and_b64 exec, exec, vcc
	v_lshlrev_b32_e32 v55, 3, v55
	v_lshlrev_b32_e32 v58, 2, v80
	v_or_b32_e32 v43, 1, v79
	v_add3_u32 v55, v96, v55, v58
	ds_write_b64 v55, v[42:43] offset:41216
.LBB0_870:
	s_or_b64 exec, exec, s[6:7]
	v_max_f32_e32 v42, 0, v52
	v_fma_f32 v42, v6, v42, 0
	v_max_f32_e32 v43, 0, v56
	v_fmac_f32_e32 v42, v7, v43
	v_max_f32_e32 v43, 0, v60
	v_fmac_f32_e32 v42, v8, v43
	v_max_f32_e32 v43, 0, v64
	v_fmac_f32_e32 v42, v9, v43
	v_max_f32_e32 v43, 0, v68
	v_fmac_f32_e32 v42, v2, v43
	v_max_f32_e32 v43, 0, v72
	v_fmac_f32_e32 v42, v3, v43
	v_max_f32_e32 v43, 0, v76
	v_fmac_f32_e32 v42, v4, v43
	v_max_f32_e32 v43, 0, v44
	v_fmac_f32_e32 v42, v5, v43
	v_ashrrev_i32_e32 v43, 31, v42
	v_bitop3_b32 v42, v43, v42, s39 bitop3:0x36
	v_lshrrev_b32_e32 v44, 12, v42
	v_cmp_eq_u32_e32 vcc, v44, v99
	s_and_b64 s[8:9], s[4:5], vcc
	s_and_saveexec_b64 s[6:7], s[8:9]
	s_cbranch_execz .LBB0_873
	ds_add_rtn_u32 v52, v136, v203 offset:49408
	s_waitcnt lgkmcnt(0)
	v_cmp_gt_u32_e32 vcc, 64, v52
	s_and_b64 exec, exec, vcc
	v_lshlrev_b32_e32 v52, 3, v52
	v_lshlrev_b32_e32 v55, 2, v80
	v_or_b32_e32 v43, 2, v79
	v_add3_u32 v52, v96, v52, v55
	ds_write_b64 v52, v[42:43] offset:41216
.LBB0_873:
	s_or_b64 exec, exec, s[6:7]
	v_max_f32_e32 v42, 0, v53
	v_fma_f32 v42, v6, v42, 0
	v_max_f32_e32 v43, 0, v57
	v_fmac_f32_e32 v42, v7, v43
	v_max_f32_e32 v43, 0, v61
	v_fmac_f32_e32 v42, v8, v43
	v_max_f32_e32 v43, 0, v65
	v_fmac_f32_e32 v42, v9, v43
	v_max_f32_e32 v43, 0, v69
	v_fmac_f32_e32 v42, v2, v43
	v_max_f32_e32 v43, 0, v73
	v_fmac_f32_e32 v42, v3, v43
	v_max_f32_e32 v43, 0, v77
	v_fmac_f32_e32 v42, v4, v43
	v_max_f32_e32 v43, 0, v45
	v_fmac_f32_e32 v42, v5, v43
	v_ashrrev_i32_e32 v43, 31, v42
	v_bitop3_b32 v42, v43, v42, s39 bitop3:0x36
	v_lshrrev_b32_e32 v45, 12, v42
	v_cmp_eq_u32_e32 vcc, v45, v99
	s_and_b64 s[6:7], s[4:5], vcc
	s_and_saveexec_b64 s[4:5], s[6:7]
	s_cbranch_execz .LBB0_876
	ds_add_rtn_u32 v52, v136, v203 offset:49408
	s_waitcnt lgkmcnt(0)
	v_cmp_gt_u32_e32 vcc, 64, v52
	s_and_b64 exec, exec, vcc
	v_lshlrev_b32_e32 v52, 3, v52
	v_lshlrev_b32_e32 v53, 2, v80
	v_or_b32_e32 v43, 3, v79
	v_add3_u32 v52, v96, v52, v53
	ds_write_b64 v52, v[42:43] offset:41216

; DI f32x4 mfma16(bf16x8 a, bf16x8 b, f32x4 c) { return __builtin_amdgcn_mfma_f32_16x16x32_bf16(a, b, c, 0, 0, 0); }
; template <int PASS, bool DIAG>
; DI void idx_tile(const bf16x8 kf, const bf16x8 (&qf)[8], const float (&wq)[8], int kt, int lm, int lg, int tq, bool selall, u32 bA, u32 pfx,
;                  u32* hist, u32* maskw, u32* cand, u32* ccnt) {
;   const f32x4 z4 = {0.f, 0.f, 0.f, 0.f};
;   f32x4 sc = z4;
; #pragma unroll
;   for (int j = 0; j < 8; ++j) {
;     f32x4 d = mfma16(kf, qf[j], z4);
; #pragma unroll
;     for (int r = 0; r < 4; ++r) sc[r] += wq[j] * fmaxf(d[r], 0.f);
;   }
;   u32 selbits = 0u;
; #pragma unroll
;   for (int r = 0; r < 4; ++r) {
;     const int key = kt * 16 + lg * 4 + r;
;     const bool valid = !DIAG || key <= tq;
;     const u32 bits = __float_as_uint(sc[r]);
;     const u32 u = bits ^ ((u32)((int)bits >> 31) | 0x80000000u);
;     if (PASS == 0) {
;       if (valid) { const u32 bin = u >> 22; atomicAdd(&hist[lm * 512 + (bin >> 1)], 1u << ((bin & 1) * 16)); }
;     } else if (PASS == 1) {
;       if (valid && (u >> 22) == bA) { const u32 bin = (u >> 12) & 1023u; atomicAdd(&hist[lm * 512 + (bin >> 1)], 1u << ((bin & 1) * 16)); }
;     } else {
;       const u32 pp = u >> 12;
;       if (valid && (selall || pp > pfx)) selbits |= 1u << r;
;       if (valid && !selall && pp == pfx) {
;         const u32 ix = atomicAdd(&ccnt[lm], 1u);
;         if (ix < 64u) { cand[(lm * 64 + ix) * 2] = u; cand[(lm * 64 + ix) * 2 + 1] = (u32)key; }
;       }
;     }
;   }
; template <int PASS>
; DI void idx_pass(const u16* kp, const bf16x8 (&qf)[8], const float (&wq)[8], int wave, int ntile, int lm, int lg, int tq, bool selall,
;                  u32 bA, u32 pfx, u32* hist, u32* maskw, u32* cand, u32* ccnt) {
;     ...
;   if (kt == ntile - 1) idx_tile<PASS, true>(ka, qf, wq, kt, lm, lg, tq, selall, bA, pfx, hist, maskw, cand, ccnt);
.LBB0_879:
	s_or_b64 exec, exec, s[2:3]
	v_cmp_eq_u32_e32 vcc, v109, v97
	s_and_saveexec_b64 s[2:3], vcc
	s_cbranch_execz .LBB0_894
	s_waitcnt vmcnt(1)
	v_mfma_f32_16x16x32_bf16 v[38:41], v[42:45], v[38:41], 0
	v_cmp_gt_u32_e32 vcc, v98, v88
	v_mfma_f32_16x16x32_bf16 v[34:37], v[42:45], v[34:37], 0
	v_mfma_f32_16x16x32_bf16 v[30:33], v[42:45], v[30:33], 0
	s_nop 4
	s_waitcnt vmcnt(0)
	v_max_f32_e32 v46, 0, v38
	v_mfma_f32_16x16x32_bf16 v[26:29], v[42:45], v[26:29], 0
	v_max_f32_e32 v47, 0, v34
	v_pk_mul_f32 v[46:47], v[6:7], v[46:47]
	v_mfma_f32_16x16x32_bf16 v[22:25], v[42:45], v[22:25], 0
	v_add_f32_e32 v0, 0, v46
	s_nop 2
	v_add_f32_e32 v0, v0, v47
	v_mfma_f32_16x16x32_bf16 v[18:21], v[42:45], v[18:21], 0
	v_max_f32_e32 v46, 0, v30
	v_max_f32_e32 v47, 0, v26
	v_pk_mul_f32 v[46:47], v[8:9], v[46:47]
	v_mfma_f32_16x16x32_bf16 v[14:17], v[42:45], v[14:17], 0
	v_add_f32_e32 v0, v0, v46
	s_nop 1
	v_mfma_f32_16x16x32_bf16 v[10:13], v[42:45], v[10:13], 0
	v_add_f32_e32 v0, v0, v47
	v_max_f32_e32 v46, 0, v22
	v_max_f32_e32 v47, 0, v18
	v_pk_mul_f32 v[46:47], v[2:3], v[46:47]
	v_add_f32_e32 v0, v0, v46
	s_nop 1
	v_add_f32_e32 v0, v0, v47
	v_max_f32_e32 v46, 0, v14
	v_max_f32_e32 v47, 0, v10
	v_pk_mul_f32 v[42:43], v[4:5], v[46:47]
	s_nop 0
	v_add_f32_e32 v0, v0, v42
	v_add_f32_e32 v0, v0, v43
	v_ashrrev_i32_e32 v10, 31, v0
	v_bitop3_b32 v42, v10, v0, s39 bitop3:0x36
	v_lshrrev_b32_e32 v0, 12, v42
	v_cmp_ne_u32_e64 s[4:5], v0, v99
	s_or_b64 s[4:5], s[40:41], s[4:5]
	v_or_b32_e32 v43, v98, v87
	s_nor_b64 s[4:5], vcc, s[4:5]
	s_and_saveexec_b64 s[6:7], s[4:5]
	s_cbranch_execz .LBB0_883
	ds_add_rtn_u32 v10, v136, v203 offset:49408
	s_waitcnt lgkmcnt(0)
	v_cmp_gt_u32_e64 s[4:5], 64, v10
	s_and_b64 exec, exec, s[4:5]
	v_lshlrev_b32_e32 v10, 3, v10
	v_lshlrev_b32_e32 v14, 2, v80
	v_add3_u32 v10, v96, v10, v14
	ds_write_b64 v10, v[42:43] offset:41216
.LBB0_883:
	s_or_b64 exec, exec, s[6:7]
	v_max_f32_e32 v10, 0, v39
	v_fma_f32 v10, v6, v10, 0
	v_max_f32_e32 v14, 0, v35
	v_fmac_f32_e32 v10, v7, v14
	v_max_f32_e32 v14, 0, v31
	v_fmac_f32_e32 v10, v8, v14
	v_max_f32_e32 v14, 0, v27
	v_fmac_f32_e32 v10, v9, v14
	v_max_f32_e32 v14, 0, v23
	v_fmac_f32_e32 v10, v2, v14
	v_max_f32_e32 v14, 0, v19
	v_fmac_f32_e32 v10, v3, v14
	v_max_f32_e32 v14, 0, v15
	v_fmac_f32_e32 v10, v4, v14
	v_max_f32_e32 v11, 0, v11
	v_fmac_f32_e32 v10, v5, v11
	v_ashrrev_i32_e32 v11, 31, v10
	v_bitop3_b32 v10, v11, v10, s39 bitop3:0x36
	v_lshrrev_b32_e32 v14, 12, v10
	v_cmp_ne_u32_e64 s[6:7], v14, v99
	v_cmp_ge_u32_e64 s[4:5], v98, v88
	s_or_b64 s[6:7], s[40:41], s[6:7]
	s_nor_b64 s[6:7], s[4:5], s[6:7]
	s_and_saveexec_b64 s[8:9], s[6:7]
	s_cbranch_execz .LBB0_886
	ds_add_rtn_u32 v15, v136, v203 offset:49408
	s_waitcnt lgkmcnt(0)
	v_cmp_gt_u32_e64 s[6:7], 64, v15
	s_and_b64 exec, exec, s[6:7]
	v_lshlrev_b32_e32 v15, 3, v15
	v_lshlrev_b32_e32 v18, 2, v80
	v_or_b32_e32 v11, 1, v43
	v_add3_u32 v15, v96, v15, v18
	ds_write_b64 v15, v[10:11] offset:41216
.LBB0_886:
	s_or_b64 exec, exec, s[8:9]
	v_max_f32_e32 v10, 0, v40
	v_fma_f32 v10, v6, v10, 0
	v_max_f32_e32 v11, 0, v36
	v_fmac_f32_e32 v10, v7, v11
	v_max_f32_e32 v11, 0, v32
	v_fmac_f32_e32 v10, v8, v11
	v_max_f32_e32 v11, 0, v28
	v_fmac_f32_e32 v10, v9, v11
	v_max_f32_e32 v11, 0, v24
	v_fmac_f32_e32 v10, v2, v11
	v_max_f32_e32 v11, 0, v20
	v_fmac_f32_e32 v10, v3, v11
	v_max_f32_e32 v11, 0, v16
	v_fmac_f32_e32 v10, v4, v11
	v_max_f32_e32 v11, 0, v12
	v_fmac_f32_e32 v10, v5, v11
	v_ashrrev_i32_e32 v12, 31, v10
	v_bitop3_b32 v10, v12, v10, s39 bitop3:0x36
	v_lshrrev_b32_e32 v12, 12, v10
	v_or_b32_e32 v11, 2, v43
	v_cmp_ne_u32_e64 s[8:9], v12, v99
	v_cmp_gt_u32_e64 s[6:7], v11, v108
	s_or_b64 s[8:9], s[40:41], s[8:9]
	s_nor_b64 s[8:9], s[6:7], s[8:9]
	s_and_saveexec_b64 s[28:29], s[8:9]
	s_cbranch_execz .LBB0_889
	ds_add_rtn_u32 v15, v136, v203 offset:49408
	s_waitcnt lgkmcnt(0)
	v_cmp_gt_u32_e64 s[8:9], 64, v15
	s_and_b64 exec, exec, s[8:9]
	v_lshlrev_b32_e32 v15, 3, v15
	v_lshlrev_b32_e32 v16, 2, v80
	v_add3_u32 v15, v96, v15, v16
	ds_write_b64 v15, v[10:11] offset:41216
.LBB0_889:
	s_or_b64 exec, exec, s[28:29]
	v_max_f32_e32 v10, 0, v41
	v_fma_f32 v6, v6, v10, 0
	v_max_f32_e32 v10, 0, v37
	v_fmac_f32_e32 v6, v7, v10
	v_max_f32_e32 v7, 0, v33
	v_fmac_f32_e32 v6, v8, v7
	v_max_f32_e32 v7, 0, v29
	v_fmac_f32_e32 v6, v9, v7
	v_max_f32_e32 v7, 0, v25
	v_fmac_f32_e32 v6, v2, v7
	v_max_f32_e32 v2, 0, v21
	v_fmac_f32_e32 v6, v3, v2
	v_max_f32_e32 v2, 0, v17
	v_fmac_f32_e32 v6, v4, v2
	v_max_f32_e32 v2, 0, v13
	v_fmac_f32_e32 v6, v5, v2
	v_ashrrev_i32_e32 v2, 31, v6
	v_bitop3_b32 v2, v2, v6, s39 bitop3:0x36
	v_lshrrev_b32_e32 v4, 12, v2
	v_or_b32_e32 v3, 3, v43
	v_cmp_ne_u32_e64 s[42:43], v4, v99
	v_cmp_gt_u32_e64 s[8:9], v3, v108
	s_or_b64 s[28:29], s[40:41], s[42:43]
	s_nor_b64 s[34:35], s[8:9], s[28:29]
	s_and_saveexec_b64 s[28:29], s[34:35]
	s_cbranch_execz .LBB0_892
	ds_add_rtn_u32 v5, v136, v203 offset:49408
	s_waitcnt lgkmcnt(0)
	v_cmp_gt_u32_e64 s[42:43], 64, v5
	s_and_b64 exec, exec, s[42:43]
	v_lshlrev_b32_e32 v5, 3, v5
	v_lshlrev_b32_e32 v6, 2, v80
	v_add3_u32 v5, v96, v5, v6
	ds_write_b64 v5, v[2:3] offset:41216

; DI void phase_resid(const Params& p, int from_x, const u16* A, int K, const u16* W, float* rowss_next, bool last,
;                     unsigned char* smem) {
;     ...
;   for (int it = vblock(); it < nfull; it += gridDim.x) {
;     const int g = it / (4 * NT), rem = it - g * (4 * NT), nt = rem >> 2, mt = g * 4 + (rem & 3);
;     f32x4 acc[8][4];
;     zero_acc<4, 8>(acc);
;     gemm_kloop<4, 8>(A + (size_t)(mt * 256) * K, K, W + (size_t)(nt * 256) * K, K, K, acc, smem);
.LBB0_959:
	s_ashr_i32 s2, s31, 31
	s_lshr_b32 s2, s2, 28
	s_add_i32 s2, s31, s2
	s_lshl_b32 s2, s2, 6
	s_and_b32 s49, s2, 0xfffffc00
	s_lshl_b32 s2, s31, 8
	v_mov_b32_e32 v52, v166
	s_and_b32 s2, s2, 0x300
	s_movk_i32 s50, 0xb00
	v_ashrrev_i32_e32 v53, 3, v52
	s_or_b32 s43, s49, s2
	v_mul_lo_u32 v2, v53, s50
	s_waitcnt lgkmcnt(0)
	v_lshlrev_b32_e32 v3, 3, v52
	s_and_b32 s48, s44, 0x300
	s_mul_i32 s2, s43, 0x1600
	v_and_or_b32 v2, v3, 56, v2
	s_mul_hi_i32 s3, s43, 0x1600
	s_add_u32 s2, s86, s2
	v_ashrrev_i32_e32 v3, 31, v2
	s_addc_u32 s3, s87, s3
	s_waitcnt vmcnt(3)
	v_lshlrev_b64 v[34:35], 1, v[2:3]
	s_lshl_b32 s42, s31, 6
	v_lshl_add_u64 v[36:37], s[2:3], 0, v[34:35]
	s_sub_i32 s42, s42, s49
	s_waitcnt vmcnt(2)
	v_add_co_u32_e32 v38, vcc, s24, v36
	s_and_b32 s42, s42, 0xffffff00
	s_nop 0
	v_addc_co_u32_e32 v39, vcc, 0, v37, vcc
	s_mul_i32 s46, s42, 0x1600
	v_add_co_u32_e32 v40, vcc, s80, v36
	s_mul_hi_i32 s47, s42, 0x1600
	s_add_u32 s46, s28, s46
	v_addc_co_u32_e32 v41, vcc, 0, v37, vcc
	s_addc_u32 s47, s29, s47
	s_waitcnt vmcnt(1)
	v_add_co_u32_e32 v42, vcc, s18, v36
	v_lshl_add_u64 v[44:45], s[46:47], 0, v[34:35]
	s_nop 0
	v_addc_co_u32_e32 v43, vcc, 0, v37, vcc
	s_waitcnt vmcnt(0)
; template <int MI, int NI>
; DI void gemm_kloop(const u16* Au, int lda, const u16* Bu, int ldb, int K, f32x4 (&acc)[NI][MI], unsigned char* smem) {
;     ...
;   GLOAD(0);
;   SWRITE(0);
; DI void phase_resid(const Params& p, int from_x, const u16* A, int K, const u16* W, float* rowss_next, bool last,
;                     unsigned char* smem) {
;     ...
;     zero_acc<4, 8>(acc);
;     gemm_kloop<4, 8>(A + (size_t)(mt * 256) * K, K, W + (size_t)(nt * 256) * K, K, K, acc, smem);
	s_mov_b64 s[88:89], s[2:3]
	s_mov_b64 s[90:91], s[46:47]
	v_lshrrev_b32_e32 v138, 3, v166
	v_lshlrev_b32_e32 v139, 4, v166
	v_xor_b32_e32 v139, v139, v166
	v_and_b32_e32 v139, 0x70, v139
	v_mul_u32_u24_e32 v255, 0x1600, v138
	v_or_b32_e32 v255, v255, v139
	v_lshrrev_b32_e32 v140, 6, v166
	s_nop 0
	v_readfirstlane_b32 s94, v140
	v_and_b32_e32 v138, 15, v166
	v_bfe_u32 v139, v166, 4, 2
	v_lshrrev_b32_e32 v140, 1, v138
	v_xor_b32_e32 v183, v139, v140
	v_or_b32_e32 v139, 4, v139
	v_xor_b32_e32 v226, v139, v140
	v_lshlrev_b32_e32 v138, 7, v138
	v_lshl_or_b32 v183, v183, 4, v138
	v_lshl_or_b32 v226, v226, 4, v138
	v_lshrrev_b32_e32 v138, 7, v166
	v_bfe_u32 v139, v166, 6, 1
	v_mul_u32_u24_e32 v139, 0x4000, v139
	v_add_u32_e32 v227, v139, v183
	v_add_u32_e32 v254, v139, v226
	v_mul_u32_u24_e32 v138, 0x2000, v138
	v_add_u32_e32 v183, v138, v183
	v_add_u32_e32 v226, v138, v226
	s_lshl_b32 s94, s94, 10
	s_mov_b32 m0, s94
	s_nop 0
	global_load_lds_dwordx4 v255, s[88:89]
	s_add_u32 m0, m0, 0x2000
	s_add_u32 s92, s88, 0x58000
	s_addc_u32 s93, s89, 0
	global_load_lds_dwordx4 v255, s[92:93]
	s_add_u32 m0, m0, 0x2000
	s_add_u32 s92, s88, 0xb0000
	s_addc_u32 s93, s89, 0
	global_load_lds_dwordx4 v255, s[92:93]
	s_add_u32 m0, m0, 0x2000
	s_add_u32 s92, s88, 0x108000
	s_addc_u32 s93, s89, 0
	global_load_lds_dwordx4 v255, s[92:93]
	s_add_u32 m0, m0, 0x2000
	s_nop 0
	global_load_lds_dwordx4 v255, s[90:91]
	s_add_u32 m0, m0, 0x2000
	s_add_u32 s92, s90, 0x58000
	s_addc_u32 s93, s91, 0
	global_load_lds_dwordx4 v255, s[92:93]
	s_add_u32 m0, m0, 0x2000
	s_add_u32 s92, s90, 0xb0000
	s_addc_u32 s93, s91, 0
	global_load_lds_dwordx4 v255, s[92:93]
	s_add_u32 m0, m0, 0x2000
	s_add_u32 s92, s90, 0x108000
	s_addc_u32 s93, s91, 0
	global_load_lds_dwordx4 v255, s[92:93]
	s_add_u32 s88, s88, 0x80
	s_addc_u32 s89, s89, 0
	s_add_u32 s90, s90, 0x80
	s_addc_u32 s91, s91, 0
	v_add_co_u32_e32 v46, vcc, s24, v44
	s_nop 0
	s_nop 0
	v_addc_co_u32_e32 v47, vcc, 0, v45, vcc
	v_add_co_u32_e32 v48, vcc, s80, v44
	s_nop 0
	s_nop 0
	v_addc_co_u32_e32 v49, vcc, 0, v45, vcc
	v_add_co_u32_e32 v50, vcc, s18, v44
	s_nop 0
	s_nop 0
	v_addc_co_u32_e32 v51, vcc, 0, v45, vcc
	s_nop 0
	s_nop 0
	s_nop 0
	s_nop 0
	s_nop 0
	s_nop 0
	s_nop 0
	s_nop 0
	s_nop 0
	s_nop 0
	s_sub_i32 s2, s34, s49
	s_and_b32 s2, s2, 0xffffff00
	s_mul_hi_i32 s3, s2, 0x1600
	s_mulk_i32 s2, 0x1600
	s_add_u32 s2, s23, s2
	s_addc_u32 s3, s21, s3
	v_lshl_add_u64 v[168:169], s[2:3], 0, v[34:35]
	s_or_b32 s2, s49, s48
	v_lshlrev_b32_e32 v58, 4, v52
	s_mul_hi_i32 s3, s2, 0x1600
	s_mulk_i32 s2, 0x1600
	v_and_b32_e32 v54, 15, v52
	v_bfe_u32 v55, v52, 1, 3
	v_lshrrev_b32_e32 v56, 4, v52
	v_bfe_u32 v57, v52, 4, 2
	v_lshlrev_b32_e32 v59, 6, v52
	v_lshlrev_b32_e32 v60, 8, v52
	v_xor_b32_e32 v52, v58, v52
	v_lshlrev_b32_e32 v53, 7, v53
	s_add_u32 s2, s86, s2
	v_lshlrev_b32_e32 v54, 7, v54
	v_bitop3_b32 v56, v56, v55, 3 bitop3:0x6c
	v_bitop3_b32 v55, v57, v55, 4 bitop3:0x36
	v_and_or_b32 v182, v52, s12, v53
	s_addc_u32 s3, s87, s3
	v_mov_b32_e32 v158, 0
	s_mov_b32 s46, 0
	v_and_b32_e32 v179, 0xffffe000, v59
	v_and_b32_e32 v181, 0x4000, v60
	v_lshl_or_b32 v180, v56, 4, v54
	v_lshl_or_b32 v178, v55, 4, v54
	v_lshl_add_u64 v[170:171], s[2:3], 0, v[34:35]
	s_mov_b64 s[2:3], 0
	v_mov_b32_e32 v159, v158
	v_mov_b32_e32 v160, v158
	v_mov_b32_e32 v161, v158
	v_mov_b32_e32 v58, v158
	v_mov_b32_e32 v59, v158
	v_mov_b32_e32 v60, v158
	v_mov_b32_e32 v61, v158
	v_mov_b32_e32 v74, v158
	v_mov_b32_e32 v75, v158
	v_mov_b32_e32 v76, v158
	v_mov_b32_e32 v77, v158
	v_mov_b32_e32 v78, v158
	v_mov_b32_e32 v79, v158
	v_mov_b32_e32 v80, v158
	v_mov_b32_e32 v81, v158
	v_mov_b32_e32 v62, v158
	v_mov_b32_e32 v63, v158
	v_mov_b32_e32 v64, v158
	v_mov_b32_e32 v65, v158
	v_mov_b32_e32 v38, v158
	v_mov_b32_e32 v39, v158
	v_mov_b32_e32 v40, v158
	v_mov_b32_e32 v41, v158
	v_mov_b32_e32 v2, v158
	v_mov_b32_e32 v3, v158
	v_mov_b32_e32 v4, v158
	v_mov_b32_e32 v5, v158
	v_mov_b32_e32 v6, v158
	v_mov_b32_e32 v7, v158
	v_mov_b32_e32 v8, v158
	v_mov_b32_e32 v9, v158
	v_mov_b32_e32 v10, v158
	v_mov_b32_e32 v11, v158
	v_mov_b32_e32 v12, v158
	v_mov_b32_e32 v13, v158
	v_mov_b32_e32 v14, v158
	v_mov_b32_e32 v15, v158
	v_mov_b32_e32 v16, v158
	v_mov_b32_e32 v17, v158
	v_mov_b32_e32 v18, v158
	v_mov_b32_e32 v19, v158
	v_mov_b32_e32 v20, v158
	v_mov_b32_e32 v21, v158
	v_mov_b32_e32 v22, v158
	v_mov_b32_e32 v23, v158
	v_mov_b32_e32 v24, v158
	v_mov_b32_e32 v25, v158
	v_mov_b32_e32 v26, v158
	v_mov_b32_e32 v27, v158
	v_mov_b32_e32 v28, v158
	v_mov_b32_e32 v29, v158
	v_mov_b32_e32 v30, v158
	v_mov_b32_e32 v31, v158
	v_mov_b32_e32 v32, v158
	v_mov_b32_e32 v33, v158
	v_mov_b32_e32 v34, v158
	v_mov_b32_e32 v35, v158
	v_mov_b32_e32 v36, v158
	v_mov_b32_e32 v37, v158
	v_mov_b32_e32 v42, v158
	v_mov_b32_e32 v43, v158
	v_mov_b32_e32 v44, v158
	v_mov_b32_e32 v45, v158
	v_mov_b32_e32 v46, v158
	v_mov_b32_e32 v47, v158
	v_mov_b32_e32 v48, v158
	v_mov_b32_e32 v49, v158
	v_mov_b32_e32 v50, v158
	v_mov_b32_e32 v51, v158
	v_mov_b32_e32 v52, v158
	v_mov_b32_e32 v53, v158
	v_mov_b32_e32 v54, v158
	v_mov_b32_e32 v55, v158
	v_mov_b32_e32 v56, v158
	v_mov_b32_e32 v57, v158
	v_mov_b32_e32 v66, v158
	v_mov_b32_e32 v67, v158
	v_mov_b32_e32 v68, v158
	v_mov_b32_e32 v69, v158
	v_mov_b32_e32 v70, v158
	v_mov_b32_e32 v71, v158
	v_mov_b32_e32 v72, v158
	v_mov_b32_e32 v73, v158
	v_mov_b32_e32 v82, v158
	v_mov_b32_e32 v83, v158
	v_mov_b32_e32 v84, v158
	v_mov_b32_e32 v85, v158
	v_mov_b32_e32 v86, v158
	v_mov_b32_e32 v87, v158
	v_mov_b32_e32 v88, v158
	v_mov_b32_e32 v89, v158
	v_mov_b32_e32 v90, v158
	v_mov_b32_e32 v91, v158
	v_mov_b32_e32 v92, v158
	v_mov_b32_e32 v93, v158
	v_mov_b32_e32 v94, v158
	v_mov_b32_e32 v95, v158
	v_mov_b32_e32 v96, v158
	v_mov_b32_e32 v97, v158
	v_mov_b32_e32 v98, v158
	v_mov_b32_e32 v99, v158
	v_mov_b32_e32 v100, v158
	v_mov_b32_e32 v101, v158
	v_mov_b32_e32 v102, v158
	v_mov_b32_e32 v103, v158
	v_mov_b32_e32 v104, v158
	v_mov_b32_e32 v105, v158
	v_mov_b32_e32 v106, v158
	v_mov_b32_e32 v107, v158
	v_mov_b32_e32 v108, v158
	v_mov_b32_e32 v109, v158
	v_mov_b32_e32 v110, v158
	v_mov_b32_e32 v111, v158
	v_mov_b32_e32 v112, v158
	v_mov_b32_e32 v113, v158
	v_mov_b32_e32 v114, v158
	v_mov_b32_e32 v115, v158
	v_mov_b32_e32 v116, v158
	v_mov_b32_e32 v117, v158
	v_mov_b32_e32 v118, v158
	v_mov_b32_e32 v119, v158
	v_mov_b32_e32 v120, v158
	v_mov_b32_e32 v121, v158
	v_mov_b32_e32 v150, v158
	v_mov_b32_e32 v151, v158
	v_mov_b32_e32 v152, v158
	v_mov_b32_e32 v153, v158
	s_mov_b32 s95, 0

; DI void phase_g1(const Params& p, int layer, unsigned char* smem) {
;     ...
;   for (int it = vblock(); it < NTILES; it += gridDim.x) {
;     const int g = it / (4 * NT), rem = it - g * (4 * NT), nt = rem >> 2, mt = g * 4 + (rem & 3);
;     f32x4 acc[8][4];
;     zero_acc<4, 8>(acc);
;     gemm_kloop<4, 8>(p.hb + (size_t)(mt * 256) * DM, DM, W + (size_t)(nt * 256) * DM, DM, DM, acc, smem);
.LBB0_1182:
	s_mul_hi_i32 s2, s58, 0x4ec4ec4f
	s_lshr_b32 s3, s2, 31
	s_ashr_i32 s2, s2, 4
	s_add_i32 s2, s2, s3
	s_mul_i32 s30, s2, 0xffffffcc
	s_lshl_b32 s48, s2, 10
	s_lshl_b32 s2, s58, 8
	s_load_dwordx16 s[60:75], s[0:1], 0xc8
	s_and_b32 s2, s2, 0x300
	v_mov_b32_e32 v50, v166
	s_or_b32 s2, s48, s2
	s_add_i32 s30, s30, s58
	v_lshlrev_b32_e32 v2, 3, v50
	s_ashr_i32 s3, s2, 31
	v_ashrrev_i32_e32 v51, 3, v50
	v_and_b32_e32 v2, 56, v2
	s_and_b32 s31, s59, 0x300
	s_waitcnt lgkmcnt(0)
	s_ashr_i32 s54, s30, 2
	s_lshl_b64 s[4:5], s[2:3], 11
	v_lshl_or_b32 v2, v51, 10, v2
	s_waitcnt lgkmcnt(0)
	s_add_u32 s28, s60, s4
	v_ashrrev_i32_e32 v3, 31, v2
	s_addc_u32 s29, s61, s5
	s_waitcnt vmcnt(3)
	v_lshlrev_b64 v[34:35], 1, v[2:3]
	v_lshl_add_u64 v[36:37], s[28:29], 0, v[34:35]
	s_lshl_b32 s4, s54, 8
	s_waitcnt vmcnt(2)
	v_add_co_u32_e32 v38, vcc, s33, v36
	s_ashr_i32 s5, s4, 31
	s_nop 0
	v_addc_co_u32_e32 v39, vcc, 0, v37, vcc
	s_lshl_b64 s[34:35], s[4:5], 11
	v_add_co_u32_e32 v40, vcc, s36, v36
	s_add_u32 s34, s23, s34
	s_nop 0
	v_addc_co_u32_e32 v41, vcc, 0, v37, vcc
	s_addc_u32 s35, s21, s35
	s_waitcnt vmcnt(1)
	v_add_co_u32_e32 v42, vcc, s37, v36
	v_lshl_add_u64 v[164:165], s[34:35], 0, v[34:35]
	s_nop 0
	v_addc_co_u32_e32 v43, vcc, 0, v37, vcc
	v_add_co_u32_e32 v44, vcc, s33, v164
	s_nop 0
	s_nop 0
	v_addc_co_u32_e32 v45, vcc, 0, v165, vcc
	s_waitcnt vmcnt(2)
; template <int MI, int NI>
; DI void gemm_kloop(const u16* Au, int lda, const u16* Bu, int ldb, int K, f32x4 (&acc)[NI][MI], unsigned char* smem) {
;     ...
;   GLOAD(0);
;   SWRITE(0);
; DI void phase_g1(const Params& p, int layer, unsigned char* smem) {
;     ...
;     f32x4 acc[8][4];
;     zero_acc<4, 8>(acc);
;     gemm_kloop<4, 8>(p.hb + (size_t)(mt * 256) * DM, DM, W + (size_t)(nt * 256) * DM, DM, DM, acc, smem);
	s_mov_b64 s[88:89], s[28:29]
	s_mov_b64 s[90:91], s[34:35]
	v_lshrrev_b32_e32 v98, 3, v166
	v_lshlrev_b32_e32 v99, 4, v166
	v_xor_b32_e32 v99, v99, v166
	v_and_b32_e32 v99, 0x70, v99
	v_lshl_or_b32 v254, v98, 11, v99
	v_lshrrev_b32_e32 v100, 6, v166
	s_nop 0
	v_readfirstlane_b32 s94, v100
	v_and_b32_e32 v98, 15, v166
	v_bfe_u32 v99, v166, 4, 2
	v_lshrrev_b32_e32 v100, 1, v98
	v_xor_b32_e32 v226, v99, v100
	v_or_b32_e32 v99, 4, v99
	v_xor_b32_e32 v227, v99, v100
	v_lshlrev_b32_e32 v98, 7, v98
	v_lshl_or_b32 v226, v226, 4, v98
	v_lshl_or_b32 v227, v227, 4, v98
	v_lshrrev_b32_e32 v98, 7, v166
	v_bfe_u32 v99, v166, 6, 1
	v_mul_u32_u24_e32 v99, 0x4000, v99
	v_add_u32_e32 v228, v99, v226
	v_add_u32_e32 v229, v99, v227
	v_mul_u32_u24_e32 v98, 0x2000, v98
	v_add_u32_e32 v226, v98, v226
	v_add_u32_e32 v227, v98, v227
	s_lshl_b32 s94, s94, 10
	s_mov_b32 m0, s94
	s_nop 0
	global_load_lds_dwordx4 v254, s[88:89]
	s_add_u32 m0, m0, 0x2000
	s_add_u32 s92, s88, 0x20000
	s_addc_u32 s93, s89, 0
	global_load_lds_dwordx4 v254, s[92:93]
	s_add_u32 m0, m0, 0x2000
	s_add_u32 s92, s88, 0x40000
	s_addc_u32 s93, s89, 0
	global_load_lds_dwordx4 v254, s[92:93]
	s_add_u32 m0, m0, 0x2000
	s_add_u32 s92, s88, 0x60000
	s_addc_u32 s93, s89, 0
	global_load_lds_dwordx4 v254, s[92:93]
	s_add_u32 m0, m0, 0x2000
	s_nop 0
	global_load_lds_dwordx4 v254, s[90:91]
	s_add_u32 m0, m0, 0x2000
	s_add_u32 s92, s90, 0x20000
	s_addc_u32 s93, s91, 0
	global_load_lds_dwordx4 v254, s[92:93]
	s_add_u32 m0, m0, 0x2000
	s_add_u32 s92, s90, 0x40000
	s_addc_u32 s93, s91, 0
	global_load_lds_dwordx4 v254, s[92:93]
	s_add_u32 m0, m0, 0x2000
	s_add_u32 s92, s90, 0x60000
	s_addc_u32 s93, s91, 0
	global_load_lds_dwordx4 v254, s[92:93]
	s_add_u32 s88, s88, 0x80
	s_addc_u32 s89, s89, 0
	s_add_u32 s90, s90, 0x80
	s_addc_u32 s91, s91, 0
	v_add_co_u32_e32 v46, vcc, s36, v164
	s_nop 0
	s_nop 0
	v_addc_co_u32_e32 v47, vcc, 0, v165, vcc
	v_add_co_u32_e32 v48, vcc, s37, v164
	s_nop 0
	s_nop 0
	v_addc_co_u32_e32 v49, vcc, 0, v165, vcc
	s_nop 0
	s_nop 0
	s_nop 0
	s_nop 0
	s_nop 0
	s_nop 0
	s_nop 0
	s_nop 0
	s_nop 0
	s_nop 0
	s_nop 0
	s_or_b32 s28, s48, s31
	v_lshlrev_b32_e32 v56, 4, v50
	s_ashr_i32 s29, s28, 31
	v_and_b32_e32 v52, 15, v50
	v_bfe_u32 v53, v50, 1, 3
	v_lshrrev_b32_e32 v54, 4, v50
	v_bfe_u32 v55, v50, 4, 2
	v_lshlrev_b32_e32 v57, 6, v50
	v_lshlrev_b32_e32 v58, 8, v50
	v_xor_b32_e32 v50, v56, v50
	v_lshlrev_b32_e32 v51, 7, v51
	s_lshl_b64 s[28:29], s[28:29], 11
	v_and_or_b32 v179, v50, s12, v51
	s_add_u32 s28, s60, s28
	v_lshlrev_b32_e32 v52, 7, v52
	v_bitop3_b32 v54, v54, v53, 3 bitop3:0x6c
	v_bitop3_b32 v53, v55, v53, 4 bitop3:0x36
	s_addc_u32 s29, s61, s29
	s_mov_b32 s3, 0
	v_and_b32_e32 v176, 0xffffe000, v57
	v_and_b32_e32 v178, 0x4000, v58
	v_lshl_or_b32 v177, v54, 4, v52
	v_lshl_or_b32 v175, v53, 4, v52
	v_lshl_add_u64 v[168:169], s[28:29], 0, v[34:35]
	s_mov_b64 s[28:29], 0
	v_mov_b32_e32 v2, 0
	v_mov_b32_e32 v3, v2
	v_mov_b32_e32 v4, v2
	v_mov_b32_e32 v5, v2
	v_mov_b32_e32 v10, v2
	v_mov_b32_e32 v11, v2
	v_mov_b32_e32 v12, v2
	v_mov_b32_e32 v13, v2
	v_mov_b32_e32 v14, v2
	v_mov_b32_e32 v15, v2
	v_mov_b32_e32 v16, v2
	v_mov_b32_e32 v17, v2
	v_mov_b32_e32 v6, v2
	v_mov_b32_e32 v7, v2
	v_mov_b32_e32 v8, v2
	v_mov_b32_e32 v9, v2
	v_mov_b32_e32 v22, v2
	v_mov_b32_e32 v23, v2
	v_mov_b32_e32 v24, v2
	v_mov_b32_e32 v25, v2
	v_mov_b32_e32 v30, v2
	v_mov_b32_e32 v31, v2
	v_mov_b32_e32 v32, v2
	v_mov_b32_e32 v33, v2
	v_mov_b32_e32 v18, v2
	v_mov_b32_e32 v19, v2
	v_mov_b32_e32 v20, v2
	v_mov_b32_e32 v21, v2
	v_mov_b32_e32 v26, v2
	v_mov_b32_e32 v27, v2
	v_mov_b32_e32 v28, v2
	v_mov_b32_e32 v29, v2
	v_mov_b32_e32 v34, v2
	v_mov_b32_e32 v35, v2
	v_mov_b32_e32 v36, v2
	v_mov_b32_e32 v37, v2
	v_mov_b32_e32 v38, v2
	v_mov_b32_e32 v39, v2
	v_mov_b32_e32 v40, v2
	v_mov_b32_e32 v41, v2
	v_mov_b32_e32 v42, v2
	v_mov_b32_e32 v43, v2
	v_mov_b32_e32 v44, v2
	v_mov_b32_e32 v45, v2
	v_mov_b32_e32 v46, v2
	v_mov_b32_e32 v47, v2
	v_mov_b32_e32 v48, v2
	v_mov_b32_e32 v49, v2
	v_mov_b32_e32 v50, v2
	v_mov_b32_e32 v51, v2
	v_mov_b32_e32 v52, v2
	v_mov_b32_e32 v53, v2
	v_mov_b32_e32 v54, v2
	v_mov_b32_e32 v55, v2
	v_mov_b32_e32 v56, v2
	v_mov_b32_e32 v57, v2
	v_mov_b32_e32 v58, v2
	v_mov_b32_e32 v59, v2
	v_mov_b32_e32 v60, v2
	v_mov_b32_e32 v61, v2
	v_mov_b32_e32 v62, v2
	v_mov_b32_e32 v63, v2
	v_mov_b32_e32 v64, v2
	v_mov_b32_e32 v65, v2
	v_mov_b32_e32 v66, v2
	v_mov_b32_e32 v67, v2
	v_mov_b32_e32 v68, v2
	v_mov_b32_e32 v69, v2
	v_mov_b32_e32 v70, v2
	v_mov_b32_e32 v71, v2
	v_mov_b32_e32 v72, v2
	v_mov_b32_e32 v73, v2
	v_mov_b32_e32 v74, v2
	v_mov_b32_e32 v75, v2
	v_mov_b32_e32 v76, v2
	v_mov_b32_e32 v77, v2
	v_mov_b32_e32 v78, v2
	v_mov_b32_e32 v79, v2
	v_mov_b32_e32 v80, v2
	v_mov_b32_e32 v81, v2
	v_mov_b32_e32 v102, v2
	v_mov_b32_e32 v103, v2
	v_mov_b32_e32 v104, v2
	v_mov_b32_e32 v105, v2
	v_mov_b32_e32 v118, v2
	v_mov_b32_e32 v119, v2
	v_mov_b32_e32 v120, v2
	v_mov_b32_e32 v121, v2
	v_mov_b32_e32 v122, v2
	v_mov_b32_e32 v123, v2
	v_mov_b32_e32 v124, v2
	v_mov_b32_e32 v125, v2
	v_mov_b32_e32 v126, v2
	v_mov_b32_e32 v127, v2
	v_mov_b32_e32 v128, v2
	v_mov_b32_e32 v129, v2
	v_mov_b32_e32 v130, v2
	v_mov_b32_e32 v131, v2
	v_mov_b32_e32 v132, v2
	v_mov_b32_e32 v133, v2
	v_mov_b32_e32 v134, v2
	v_mov_b32_e32 v135, v2
	v_mov_b32_e32 v136, v2
	v_mov_b32_e32 v137, v2
	v_mov_b32_e32 v138, v2
	v_mov_b32_e32 v139, v2
	v_mov_b32_e32 v140, v2
	v_mov_b32_e32 v141, v2
	v_mov_b32_e32 v142, v2
	v_mov_b32_e32 v143, v2
	v_mov_b32_e32 v144, v2
	v_mov_b32_e32 v145, v2
	v_mov_b32_e32 v146, v2
	v_mov_b32_e32 v147, v2
	v_mov_b32_e32 v148, v2
	v_mov_b32_e32 v149, v2
	v_mov_b32_e32 v154, v2
	v_mov_b32_e32 v155, v2
	v_mov_b32_e32 v156, v2
	v_mov_b32_e32 v157, v2
	v_mov_b32_e32 v150, v2
	v_mov_b32_e32 v151, v2
	v_mov_b32_e32 v152, v2
	v_mov_b32_e32 v153, v2
	v_mov_b32_e32 v158, v2
	v_mov_b32_e32 v159, v2
	v_mov_b32_e32 v160, v2
	v_mov_b32_e32 v161, v2
	s_mov_b32 s95, 0
